# FFN down-projection K loop: LDS fragment reads of the next k-step issued under the current MFMAs (A reloaded in place, B double-buffered)
# speedup vs baseline: 1.0488x; 1.0081x over previous
; template <int DQK, int DV, bool NA>
; DI void attend(const bf16_t* __restrict__ Q, int q0, const bf16_t* __restrict__ Kb, const bf16_t* __restrict__ Vb,
;                int s0, int n0, int s1, int n1, f32x16 (&o)[DV / 32], char* smem, NAInfo na) {
;     ...
;                     for (int s = 0; s < NS; ++s) kf[s] = *(const bf16x8*)(sK + (sub * 32 + l31) * KS + (s * 16 + hh * 8) * 2);
;                     __builtin_amdgcn_sched_barrier(0);
; #pragma unroll
;                     for (int s = 0; s < NS; ++s) st = mfma32(kf[s], qf[s], st);
;                 }
;                 bf16x8 vf[NDT][2];
; #pragma unroll
;                 for (int d = 0; d < NDT; ++d)
; #pragma unroll
;                     for (int s2 = 0; s2 < 2; ++s2) {
;                         const char* vp = sV + (sub * 32 + 16 * s2 + 4 * hh + q) * VS + (d * 32 + dblk * 16 + 4 * p) * 2;
;                         vf[d][s2] = cat8(tr_read(vp), tr_read(vp + 8 * VS));
;                     }
;                 if (NA && t < n0) {
;                     const float* brow = rpb + (kr - na.qr + 7) * 31 + 15 - qc;
; #pragma unroll
;                     for (int r = 0; r < 16; ++r) {
;                         const int kc = sub * 32 + (r & 3) + 8 * (r >> 2) + 4 * hh;
;                         const bool valid = (kc >= cs) && (kc < cs + 16);
;                         const int bi = valid ? kc : cs;
;                         const float bias = brow[bi];
;                         st[r] = valid ? st[r] + bias : -INFINITY;
;                     }
;                 }
;                 float mx = st[0];
; #pragma unroll
;                 for (int r = 1; r < 16; ++r) mx = fmaxf(mx, st[r]);
;                 mx = xor32_max(mx);
;                 float rsum = 0.f;
;                 if (NA) {
;                     const float mnew = fmaxf(m, mx);
;                     const float muse = (mnew == -INFINITY) ? 0.f : mnew;
;                     const float alpha = __builtin_amdgcn_exp2f(m - muse);
;                     m = mnew;
;                     l *= alpha;
; #pragma unroll
;                     for (int d = 0; d < NDT; ++d)
; #pragma unroll
;                         for (int r = 0; r < 16; ++r) o[d][r] *= alpha;
; #pragma unroll
;                     for (int r = 0; r < 16; ++r) { st[r] = __builtin_amdgcn_exp2f(st[r] - muse); rsum += st[r]; }
;                 } else {
.LBB0_109:
	s_add_i32 s2, s2, 1
	s_and_b32 s3, s2, 1
	s_mul_i32 s4, s3, 0x8400
	v_add_u32_e32 v154, s4, v172
	v_add_u32_e32 v155, s4, v152
	v_add_u32_e32 v154, v154, v151
	v_add_u32_e32 v155, v155, v150
	ds_read_b128 v[116:119], v154
	ds_read_b128 v[120:123], v154 offset:32
	ds_read_b128 v[124:127], v154 offset:64
	ds_read_b128 v[128:131], v154 offset:96
	ds_read_b128 v[156:159], v154 offset:128
	ds_read_b128 v[160:163], v154 offset:160
	s_waitcnt lgkmcnt(5)
	v_mfma_f32_32x32x16_bf16 v[64:79], v[116:119], v[100:103], v[48:63]
	ds_read_b128 v[116:119], v154 offset:6656
	s_waitcnt lgkmcnt(5)
	v_mfma_f32_32x32x16_bf16 v[64:79], v[120:123], v[96:99], v[64:79]
	ds_read_b128 v[120:123], v154 offset:6688
	s_waitcnt lgkmcnt(5)
	v_mfma_f32_32x32x16_bf16 v[64:79], v[124:127], v[92:95], v[64:79]
	ds_read_b128 v[124:127], v154 offset:6720
	s_waitcnt lgkmcnt(5)
	v_mfma_f32_32x32x16_bf16 v[64:79], v[128:131], v[88:91], v[64:79]
	ds_read_b128 v[128:131], v154 offset:6752
	s_waitcnt lgkmcnt(5)
	v_mfma_f32_32x32x16_bf16 v[64:79], v[156:159], v[84:87], v[64:79]
	ds_read_b128 v[156:159], v154 offset:6784
	s_waitcnt lgkmcnt(5)
	v_mfma_f32_32x32x16_bf16 v[64:79], v[160:163], v[80:83], v[64:79]
	ds_read_b128 v[160:163], v154 offset:6816
	ds_read_b64_tr_b16 v[242:243], v155 offset:13312
	ds_read_b64_tr_b16 v[244:245], v155 offset:14848
	ds_read_b64_tr_b16 v[246:247], v155 offset:13376
	ds_read_b64_tr_b16 v[248:249], v155 offset:14912
	s_nop 6
	v_max3_f32 v237, v64, v65, v66
	v_max3_f32 v238, v72, v73, v74
	v_max3_f32 v237, v237, v67, v68
	v_max3_f32 v238, v238, v75, v76
	v_max3_f32 v237, v237, v69, v70
	v_max3_f32 v238, v238, v77, v78
	v_max3_f32 v237, v237, v71, v79
	v_max_f32_e32 v237, v237, v238
	v_cmp_lt_f32_e32 vcc, 0x41000000, v237
	s_cbranch_vccnz .Lmy_mla_rare0
.Lmy_mla_res0:
	s_waitcnt lgkmcnt(9)
	v_mfma_f32_32x32x16_bf16 v[32:47], v[116:119], v[100:103], v[48:63]
	v_exp_f32_e32 v64, v64
	v_exp_f32_e32 v65, v65
	v_exp_f32_e32 v66, v66
	v_exp_f32_e32 v67, v67
	v_exp_f32_e32 v68, v68
	v_exp_f32_e32 v69, v69
	v_exp_f32_e32 v70, v70
	s_waitcnt lgkmcnt(8)
	v_mfma_f32_32x32x16_bf16 v[32:47], v[120:123], v[96:99], v[32:47]
	v_exp_f32_e32 v71, v71
	v_add_f32_e32 v250, v64, v65
	v_add_f32_e32 v250, v250, v66
	v_add_f32_e32 v250, v250, v67
	v_add_f32_e32 v250, v250, v68
	v_add_f32_e32 v250, v250, v69
	v_add_f32_e32 v250, v250, v70
	s_waitcnt lgkmcnt(7)
	v_mfma_f32_32x32x16_bf16 v[32:47], v[124:127], v[92:95], v[32:47]
	v_add_f32_e32 v250, v250, v71
	v_cvt_pk_bf16_f32 v64, v64, v65
	v_cvt_pk_bf16_f32 v65, v66, v67
	v_cvt_pk_bf16_f32 v66, v68, v69
	v_cvt_pk_bf16_f32 v67, v70, v71
	v_exp_f32_e32 v72, v72
	s_waitcnt lgkmcnt(6)
	v_mfma_f32_32x32x16_bf16 v[32:47], v[128:131], v[88:91], v[32:47]
	v_exp_f32_e32 v73, v73
	v_exp_f32_e32 v74, v74
	v_exp_f32_e32 v75, v75
	v_exp_f32_e32 v76, v76
	v_exp_f32_e32 v77, v77
	v_exp_f32_e32 v78, v78
	s_waitcnt lgkmcnt(5)
	v_mfma_f32_32x32x16_bf16 v[32:47], v[156:159], v[84:87], v[32:47]
	v_exp_f32_e32 v79, v79
	v_add_f32_e32 v251, v72, v73
	v_add_f32_e32 v251, v251, v74
	v_add_f32_e32 v251, v251, v75
	v_add_f32_e32 v251, v251, v76
	v_add_f32_e32 v251, v251, v77
	s_waitcnt lgkmcnt(4)
	v_mfma_f32_32x32x16_bf16 v[32:47], v[160:163], v[80:83], v[32:47]
	v_add_f32_e32 v251, v251, v78
	v_add_f32_e32 v251, v251, v79
	v_cvt_pk_bf16_f32 v72, v72, v73
	v_cvt_pk_bf16_f32 v73, v74, v75
	v_cvt_pk_bf16_f32 v74, v76, v77
	v_cvt_pk_bf16_f32 v75, v78, v79
	ds_read_b64_tr_b16 v[116:117], v155 offset:16384
	ds_read_b64_tr_b16 v[118:119], v155 offset:17920
	ds_read_b64_tr_b16 v[120:121], v155 offset:16448
	ds_read_b64_tr_b16 v[122:123], v155 offset:17984
	s_waitcnt lgkmcnt(4)
	v_mfma_f32_32x32x16_bf16 v[16:31], v[242:245], v[64:67], v[16:31]
	ds_read_b64_tr_b16 v[242:243], v155 offset:19456
	ds_read_b64_tr_b16 v[244:245], v155 offset:20992
	v_mfma_f32_32x32x16_bf16 v[0:15], v[246:249], v[64:67], v[0:15]
	ds_read_b64_tr_b16 v[246:247], v155 offset:19520
	ds_read_b64_tr_b16 v[248:249], v155 offset:21056
	v_max3_f32 v237, v32, v33, v34
	v_max3_f32 v238, v40, v41, v42
	v_max3_f32 v237, v237, v35, v36
	s_waitcnt lgkmcnt(4)
	v_mfma_f32_32x32x16_bf16 v[16:31], v[116:119], v[72:75], v[16:31]
	ds_read_b64_tr_b16 v[116:117], v155 offset:22528
	ds_read_b64_tr_b16 v[118:119], v155 offset:24064
	v_max3_f32 v238, v238, v43, v44
	v_max3_f32 v237, v237, v37, v38
	v_max3_f32 v238, v238, v45, v46
	v_mfma_f32_32x32x16_bf16 v[0:15], v[120:123], v[72:75], v[0:15]
	ds_read_b64_tr_b16 v[120:121], v155 offset:22592
	ds_read_b64_tr_b16 v[122:123], v155 offset:24128
	v_max3_f32 v237, v237, v39, v47
	v_max_f32_e32 v237, v237, v238
	v_cmp_lt_f32_e32 vcc, 0x41000000, v237
	s_cbranch_vccnz .Lmy_mla_rare1

; template <int DQK, int DV, bool NA>
; DI void attend(const bf16_t* __restrict__ Q, int q0, const bf16_t* __restrict__ Kb, const bf16_t* __restrict__ Vb,
;                int s0, int n0, int s1, int n1, f32x16 (&o)[DV / 32], char* smem, NAInfo na) {
;     ...
;                     const bool first = (t == 0) && (sub == 0);
;                     if (first || __builtin_amdgcn_ballot_w64(mx > 8.f) != 0) {
;                         const float delta = first ? mx : fmaxf(mx, 0.f);
;                         const float alpha = first ? 1.f : __builtin_amdgcn_exp2f(-delta);
;                         m += delta;
;                         l *= alpha;
; #pragma unroll
;                         for (int d = 0; d < NDT; ++d)
; #pragma unroll
;                             for (int r = 0; r < 16; ++r) o[d][r] *= alpha;
; #pragma unroll
;                         for (int r = 0; r < 16; ++r) { st[r] -= delta; cinit[r] = -m; }
;                     }
.Lmy_mla_rare0:
	v_mov_b32_e32 v238, v237
	s_nop 1
	v_permlane32_swap_b32_e32 v237, v238
	v_max_f32_e32 v237, v237, v238
	v_max_f32_e32 v239, 0, v237
	v_exp_f32_e64 v240, -v239
	v_add_f32_e32 v133, v133, v239
	v_sub_f32_e32 v64, v64, v239
	v_sub_f32_e32 v65, v65, v239
	v_sub_f32_e32 v66, v66, v239
	v_sub_f32_e32 v67, v67, v239
	v_sub_f32_e32 v68, v68, v239
	v_sub_f32_e32 v69, v69, v239
	v_sub_f32_e32 v70, v70, v239
	v_sub_f32_e32 v71, v71, v239
	v_sub_f32_e32 v72, v72, v239
	v_sub_f32_e32 v73, v73, v239
	v_sub_f32_e32 v74, v74, v239
	v_sub_f32_e32 v75, v75, v239
	v_sub_f32_e32 v76, v76, v239
	v_sub_f32_e32 v77, v77, v239
	v_sub_f32_e32 v78, v78, v239
	v_sub_f32_e32 v79, v79, v239
	v_pk_mul_f32 v[16:17], v[16:17], v[240:241] op_sel_hi:[1,0]
	v_pk_mul_f32 v[18:19], v[18:19], v[240:241] op_sel_hi:[1,0]
	v_pk_mul_f32 v[20:21], v[20:21], v[240:241] op_sel_hi:[1,0]
	v_pk_mul_f32 v[22:23], v[22:23], v[240:241] op_sel_hi:[1,0]
	v_pk_mul_f32 v[24:25], v[24:25], v[240:241] op_sel_hi:[1,0]
	v_pk_mul_f32 v[26:27], v[26:27], v[240:241] op_sel_hi:[1,0]
	v_pk_mul_f32 v[28:29], v[28:29], v[240:241] op_sel_hi:[1,0]
	v_pk_mul_f32 v[30:31], v[30:31], v[240:241] op_sel_hi:[1,0]
	v_pk_mul_f32 v[0:1], v[0:1], v[240:241] op_sel_hi:[1,0]
	v_pk_mul_f32 v[2:3], v[2:3], v[240:241] op_sel_hi:[1,0]
	v_pk_mul_f32 v[4:5], v[4:5], v[240:241] op_sel_hi:[1,0]
	v_pk_mul_f32 v[6:7], v[6:7], v[240:241] op_sel_hi:[1,0]
	v_pk_mul_f32 v[8:9], v[8:9], v[240:241] op_sel_hi:[1,0]
	v_pk_mul_f32 v[10:11], v[10:11], v[240:241] op_sel_hi:[1,0]
	v_pk_mul_f32 v[12:13], v[12:13], v[240:241] op_sel_hi:[1,0]
	v_pk_mul_f32 v[14:15], v[14:15], v[240:241] op_sel_hi:[1,0]
	v_mul_f32_e32 v132, v132, v240
	v_xor_b32_e32 v48, 0x80000000, v133
	v_mov_b32_e32 v49, v48
	v_mov_b32_e32 v50, v48
	v_mov_b32_e32 v51, v48
	v_mov_b32_e32 v52, v48
	v_mov_b32_e32 v53, v48
	v_mov_b32_e32 v54, v48
	v_mov_b32_e32 v55, v48
	v_mov_b32_e32 v56, v48
	v_mov_b32_e32 v57, v48
	v_mov_b32_e32 v58, v48
	v_mov_b32_e32 v59, v48
	v_mov_b32_e32 v60, v48
	v_mov_b32_e32 v61, v48
	v_mov_b32_e32 v62, v48
	v_mov_b32_e32 v63, v48
	s_nop 1
	s_branch .Lmy_mla_res0
.Lmy_mla_rare1:
	s_nop 11
	v_mov_b32_e32 v238, v237
	s_nop 1
	v_permlane32_swap_b32_e32 v237, v238
	v_max_f32_e32 v237, v237, v238
	v_max_f32_e32 v239, 0, v237
	v_exp_f32_e64 v240, -v239
	v_add_f32_e32 v133, v133, v239
	v_sub_f32_e32 v32, v32, v239
	v_sub_f32_e32 v33, v33, v239
	v_sub_f32_e32 v34, v34, v239
	v_sub_f32_e32 v35, v35, v239
	v_sub_f32_e32 v36, v36, v239
	v_sub_f32_e32 v37, v37, v239
	v_sub_f32_e32 v38, v38, v239
	v_sub_f32_e32 v39, v39, v239
	v_sub_f32_e32 v40, v40, v239
	v_sub_f32_e32 v41, v41, v239
	v_sub_f32_e32 v42, v42, v239
	v_sub_f32_e32 v43, v43, v239
	v_sub_f32_e32 v44, v44, v239
	v_sub_f32_e32 v45, v45, v239
	v_sub_f32_e32 v46, v46, v239
	v_sub_f32_e32 v47, v47, v239
	v_pk_mul_f32 v[16:17], v[16:17], v[240:241] op_sel_hi:[1,0]
	v_pk_mul_f32 v[18:19], v[18:19], v[240:241] op_sel_hi:[1,0]
	v_pk_mul_f32 v[20:21], v[20:21], v[240:241] op_sel_hi:[1,0]
	v_pk_mul_f32 v[22:23], v[22:23], v[240:241] op_sel_hi:[1,0]
	v_pk_mul_f32 v[24:25], v[24:25], v[240:241] op_sel_hi:[1,0]
	v_pk_mul_f32 v[26:27], v[26:27], v[240:241] op_sel_hi:[1,0]
	v_pk_mul_f32 v[28:29], v[28:29], v[240:241] op_sel_hi:[1,0]
	v_pk_mul_f32 v[30:31], v[30:31], v[240:241] op_sel_hi:[1,0]
	v_pk_mul_f32 v[0:1], v[0:1], v[240:241] op_sel_hi:[1,0]
	v_pk_mul_f32 v[2:3], v[2:3], v[240:241] op_sel_hi:[1,0]
	v_pk_mul_f32 v[4:5], v[4:5], v[240:241] op_sel_hi:[1,0]
	v_pk_mul_f32 v[6:7], v[6:7], v[240:241] op_sel_hi:[1,0]
	v_pk_mul_f32 v[8:9], v[8:9], v[240:241] op_sel_hi:[1,0]
	v_pk_mul_f32 v[10:11], v[10:11], v[240:241] op_sel_hi:[1,0]
	v_pk_mul_f32 v[12:13], v[12:13], v[240:241] op_sel_hi:[1,0]
	v_pk_mul_f32 v[14:15], v[14:15], v[240:241] op_sel_hi:[1,0]
	v_mul_f32_e32 v132, v132, v240
	v_xor_b32_e32 v48, 0x80000000, v133
	v_mov_b32_e32 v49, v48
	v_mov_b32_e32 v50, v48
	v_mov_b32_e32 v51, v48
	v_mov_b32_e32 v52, v48
	v_mov_b32_e32 v53, v48
	v_mov_b32_e32 v54, v48
	v_mov_b32_e32 v55, v48
	v_mov_b32_e32 v56, v48
	v_mov_b32_e32 v57, v48
	v_mov_b32_e32 v58, v48
	v_mov_b32_e32 v59, v48
	v_mov_b32_e32 v60, v48
	v_mov_b32_e32 v61, v48
	v_mov_b32_e32 v62, v48
	v_mov_b32_e32 v63, v48
	s_nop 1
	s_branch .Lmy_mla_res1

; template <int DQK, int DV, bool NA>
; DI void attend(const bf16_t* __restrict__ Q, int q0, const bf16_t* __restrict__ Kb, const bf16_t* __restrict__ Vb,
;                int s0, int n0, int s1, int n1, f32x16 (&o)[DV / 32], char* smem, NAInfo na) {
;     ...
;                     for (int s = 0; s < NS; ++s) kf[s] = *(const bf16x8*)(sK + (sub * 32 + l31) * KS + (s * 16 + hh * 8) * 2);
;                     __builtin_amdgcn_sched_barrier(0);
; #pragma unroll
;                     for (int s = 0; s < NS; ++s) st = mfma32(kf[s], qf[s], st);
;                 }
;                 bf16x8 vf[NDT][2];
; #pragma unroll
;                 for (int d = 0; d < NDT; ++d)
; #pragma unroll
;                     for (int s2 = 0; s2 < 2; ++s2) {
;                         const char* vp = sV + (sub * 32 + 16 * s2 + 4 * hh + q) * VS + (d * 32 + dblk * 16 + 4 * p) * 2;
;                         vf[d][s2] = cat8(tr_read(vp), tr_read(vp + 8 * VS));
;                     }
;                 if (NA && t < n0) {
;                     const float* brow = rpb + (kr - na.qr + 7) * 31 + 15 - qc;
; #pragma unroll
;                     for (int r = 0; r < 16; ++r) {
;                         const int kc = sub * 32 + (r & 3) + 8 * (r >> 2) + 4 * hh;
;                         const bool valid = (kc >= cs) && (kc < cs + 16);
;                         const int bi = valid ? kc : cs;
;                         const float bias = brow[bi];
;                         st[r] = valid ? st[r] + bias : -INFINITY;
;                     }
;                 }
;                 float mx = st[0];
; #pragma unroll
;                 for (int r = 1; r < 16; ++r) mx = fmaxf(mx, st[r]);
;                 mx = xor32_max(mx);
;                 float rsum = 0.f;
;                 if (NA) {
;                     const float mnew = fmaxf(m, mx);
;                     const float muse = (mnew == -INFINITY) ? 0.f : mnew;
;                     const float alpha = __builtin_amdgcn_exp2f(m - muse);
;                     m = mnew;
;                     l *= alpha;
; #pragma unroll
;                     for (int d = 0; d < NDT; ++d)
; #pragma unroll
;                         for (int r = 0; r < 16; ++r) o[d][r] *= alpha;
; #pragma unroll
;                     for (int r = 0; r < 16; ++r) { st[r] = __builtin_amdgcn_exp2f(st[r] - muse); rsum += st[r]; }
;                 } else {
.LBB0_132:
	s_add_i32 s0, s0, 1
	s_and_b32 s1, s0, 1
	s_mul_i32 s2, s1, 0x8400
	v_add_u32_e32 v238, s2, v172
	v_add_u32_e32 v237, s2, v236
	v_add_u32_e32 v238, v238, v234
	v_add_u32_e32 v237, v237, v235
	ds_read_b128 v[140:143], v238
	ds_read_b128 v[144:147], v238 offset:32
	ds_read_b128 v[148:151], v238 offset:64
	ds_read_b128 v[152:155], v238 offset:96
	s_waitcnt lgkmcnt(3)
	v_mfma_f32_32x32x16_bf16 v[96:111], v[140:143], v[120:123], v[80:95]
	ds_read_b128 v[140:143], v238 offset:4608
	s_waitcnt lgkmcnt(3)
	v_mfma_f32_32x32x16_bf16 v[96:111], v[144:147], v[124:127], v[96:111]
	ds_read_b128 v[144:147], v238 offset:4640
	s_waitcnt lgkmcnt(3)
	v_mfma_f32_32x32x16_bf16 v[96:111], v[148:151], v[116:119], v[96:111]
	ds_read_b128 v[148:151], v238 offset:4672
	s_waitcnt lgkmcnt(3)
	v_mfma_f32_32x32x16_bf16 v[96:111], v[152:155], v[112:115], v[96:111]
	ds_read_b128 v[152:155], v238 offset:4704
	ds_read_b64_tr_b16 v[156:157], v237 offset:9216
	ds_read_b64_tr_b16 v[158:159], v237 offset:11776
	ds_read_b64_tr_b16 v[160:161], v237 offset:9280
	ds_read_b64_tr_b16 v[162:163], v237 offset:11840
	ds_read_b64_tr_b16 v[164:165], v237 offset:9344
	ds_read_b64_tr_b16 v[166:167], v237 offset:11904
	ds_read_b64_tr_b16 v[168:169], v237 offset:9408
	ds_read_b64_tr_b16 v[170:171], v237 offset:11968
	s_nop 2
	v_max3_f32 v239, v96, v97, v98
	v_max3_f32 v240, v104, v105, v106
	v_max3_f32 v239, v239, v99, v100
	v_max3_f32 v240, v240, v107, v108
	v_max3_f32 v239, v239, v101, v102
	v_max3_f32 v240, v240, v109, v110
	v_max3_f32 v239, v239, v103, v111
	v_max_f32_e32 v239, v239, v240
	v_cmp_lt_f32_e32 vcc, 0x41000000, v239
	s_cbranch_vccnz .Lmy_d1_rare0
.Lmy_d1_res0:
	s_waitcnt lgkmcnt(11)
	v_mfma_f32_32x32x16_bf16 v[64:79], v[140:143], v[120:123], v[80:95]
	v_exp_f32_e32 v96, v96
	v_exp_f32_e32 v97, v97
	v_exp_f32_e32 v98, v98
	v_exp_f32_e32 v99, v99
	v_exp_f32_e32 v100, v100
	v_exp_f32_e32 v101, v101
	v_exp_f32_e32 v102, v102
	v_exp_f32_e32 v103, v103
	v_add_f32_e32 v244, v96, v97
	v_add_f32_e32 v244, v244, v98
	s_waitcnt lgkmcnt(10)
	v_mfma_f32_32x32x16_bf16 v[64:79], v[144:147], v[124:127], v[64:79]
	v_add_f32_e32 v244, v244, v99
	v_add_f32_e32 v244, v244, v100
	v_add_f32_e32 v244, v244, v101
	v_add_f32_e32 v244, v244, v102
	v_add_f32_e32 v244, v244, v103
	v_cvt_pk_bf16_f32 v96, v96, v97
	v_cvt_pk_bf16_f32 v97, v98, v99
	v_cvt_pk_bf16_f32 v98, v100, v101
	v_cvt_pk_bf16_f32 v99, v102, v103
	v_exp_f32_e32 v104, v104
	s_waitcnt lgkmcnt(9)
	v_mfma_f32_32x32x16_bf16 v[64:79], v[148:151], v[116:119], v[64:79]
	v_exp_f32_e32 v105, v105
	v_exp_f32_e32 v106, v106
	v_exp_f32_e32 v107, v107
	v_exp_f32_e32 v108, v108
	v_exp_f32_e32 v109, v109
	v_exp_f32_e32 v110, v110
	v_exp_f32_e32 v111, v111
	v_add_f32_e32 v245, v104, v105
	v_add_f32_e32 v245, v245, v106
	s_waitcnt lgkmcnt(8)
	v_mfma_f32_32x32x16_bf16 v[64:79], v[152:155], v[112:115], v[64:79]
	v_add_f32_e32 v245, v245, v107
	v_add_f32_e32 v245, v245, v108
	v_add_f32_e32 v245, v245, v109
	v_add_f32_e32 v245, v245, v110
	v_add_f32_e32 v245, v245, v111
	v_cvt_pk_bf16_f32 v104, v104, v105
	v_cvt_pk_bf16_f32 v105, v106, v107
	v_cvt_pk_bf16_f32 v106, v108, v109
	v_cvt_pk_bf16_f32 v107, v110, v111
	ds_read_b64_tr_b16 v[140:141], v237 offset:14336
	ds_read_b64_tr_b16 v[142:143], v237 offset:16896
	ds_read_b64_tr_b16 v[144:145], v237 offset:14400
	ds_read_b64_tr_b16 v[146:147], v237 offset:16960
	ds_read_b64_tr_b16 v[148:149], v237 offset:14464
	ds_read_b64_tr_b16 v[150:151], v237 offset:17024
	ds_read_b64_tr_b16 v[152:153], v237 offset:14528
	ds_read_b64_tr_b16 v[154:155], v237 offset:17088
	s_waitcnt lgkmcnt(8)
	v_mfma_f32_32x32x16_bf16 v[48:63], v[156:159], v[96:99], v[48:63]
	ds_read_b64_tr_b16 v[156:157], v237 offset:19456
	ds_read_b64_tr_b16 v[158:159], v237 offset:22016
	v_mfma_f32_32x32x16_bf16 v[32:47], v[160:163], v[96:99], v[32:47]
	ds_read_b64_tr_b16 v[160:161], v237 offset:19520
	ds_read_b64_tr_b16 v[162:163], v237 offset:22080
	v_max3_f32 v239, v64, v65, v66
	v_max3_f32 v240, v72, v73, v74
	v_mfma_f32_32x32x16_bf16 v[16:31], v[164:167], v[96:99], v[16:31]
	ds_read_b64_tr_b16 v[164:165], v237 offset:19584
	ds_read_b64_tr_b16 v[166:167], v237 offset:22144
	v_max3_f32 v239, v239, v67, v68
	v_mfma_f32_32x32x16_bf16 v[0:15], v[168:171], v[96:99], v[0:15]
	ds_read_b64_tr_b16 v[168:169], v237 offset:19648
	ds_read_b64_tr_b16 v[170:171], v237 offset:22208
	v_max3_f32 v240, v240, v75, v76
	s_waitcnt lgkmcnt(8)
	v_mfma_f32_32x32x16_bf16 v[48:63], v[140:143], v[104:107], v[48:63]
	ds_read_b64_tr_b16 v[140:141], v237 offset:24576
	ds_read_b64_tr_b16 v[142:143], v237 offset:27136
	v_max3_f32 v239, v239, v69, v70
	v_mfma_f32_32x32x16_bf16 v[32:47], v[144:147], v[104:107], v[32:47]
	ds_read_b64_tr_b16 v[144:145], v237 offset:24640
	ds_read_b64_tr_b16 v[146:147], v237 offset:27200
	v_max3_f32 v240, v240, v77, v78
	v_mfma_f32_32x32x16_bf16 v[16:31], v[148:151], v[104:107], v[16:31]
	ds_read_b64_tr_b16 v[148:149], v237 offset:24704
	ds_read_b64_tr_b16 v[150:151], v237 offset:27264
	v_max3_f32 v239, v239, v71, v79
	v_mfma_f32_32x32x16_bf16 v[0:15], v[152:155], v[104:107], v[0:15]
	ds_read_b64_tr_b16 v[152:153], v237 offset:24768
	ds_read_b64_tr_b16 v[154:155], v237 offset:27328
	v_max_f32_e32 v239, v239, v240
	v_cmp_lt_f32_e32 vcc, 0x41000000, v239
	s_cbranch_vccnz .Lmy_d1_rare1

; template <int DQK, int DV, bool NA>
; DI void attend(const bf16_t* __restrict__ Q, int q0, const bf16_t* __restrict__ Kb, const bf16_t* __restrict__ Vb,
;                int s0, int n0, int s1, int n1, f32x16 (&o)[DV / 32], char* smem, NAInfo na) {
;     ...
;                     const bool first = (t == 0) && (sub == 0);
;                     if (first || __builtin_amdgcn_ballot_w64(mx > 8.f) != 0) {
;                         const float delta = first ? mx : fmaxf(mx, 0.f);
;                         const float alpha = first ? 1.f : __builtin_amdgcn_exp2f(-delta);
;                         m += delta;
;                         l *= alpha;
; #pragma unroll
;                         for (int d = 0; d < NDT; ++d)
; #pragma unroll
;                             for (int r = 0; r < 16; ++r) o[d][r] *= alpha;
; #pragma unroll
;                         for (int r = 0; r < 16; ++r) { st[r] -= delta; cinit[r] = -m; }
;                     }
.Lmy_d1_rare0:
	v_mov_b32_e32 v240, v239
	s_nop 1
	v_permlane32_swap_b32_e32 v239, v240
	v_max_f32_e32 v239, v239, v240
	v_max_f32_e32 v241, 0, v239
	v_exp_f32_e64 v242, -v241
	v_add_f32_e32 v183, v183, v241
	v_sub_f32_e32 v96, v96, v241
	v_sub_f32_e32 v97, v97, v241
	v_sub_f32_e32 v98, v98, v241
	v_sub_f32_e32 v99, v99, v241
	v_sub_f32_e32 v100, v100, v241
	v_sub_f32_e32 v101, v101, v241
	v_sub_f32_e32 v102, v102, v241
	v_sub_f32_e32 v103, v103, v241
	v_sub_f32_e32 v104, v104, v241
	v_sub_f32_e32 v105, v105, v241
	v_sub_f32_e32 v106, v106, v241
	v_sub_f32_e32 v107, v107, v241
	v_sub_f32_e32 v108, v108, v241
	v_sub_f32_e32 v109, v109, v241
	v_sub_f32_e32 v110, v110, v241
	v_sub_f32_e32 v111, v111, v241
	v_pk_mul_f32 v[48:49], v[48:49], v[242:243] op_sel_hi:[1,0]
	v_pk_mul_f32 v[50:51], v[50:51], v[242:243] op_sel_hi:[1,0]
	v_pk_mul_f32 v[52:53], v[52:53], v[242:243] op_sel_hi:[1,0]
	v_pk_mul_f32 v[54:55], v[54:55], v[242:243] op_sel_hi:[1,0]
	v_pk_mul_f32 v[56:57], v[56:57], v[242:243] op_sel_hi:[1,0]
	v_pk_mul_f32 v[58:59], v[58:59], v[242:243] op_sel_hi:[1,0]
	v_pk_mul_f32 v[60:61], v[60:61], v[242:243] op_sel_hi:[1,0]
	v_pk_mul_f32 v[62:63], v[62:63], v[242:243] op_sel_hi:[1,0]
	v_pk_mul_f32 v[32:33], v[32:33], v[242:243] op_sel_hi:[1,0]
	v_pk_mul_f32 v[34:35], v[34:35], v[242:243] op_sel_hi:[1,0]
	v_pk_mul_f32 v[36:37], v[36:37], v[242:243] op_sel_hi:[1,0]
	v_pk_mul_f32 v[38:39], v[38:39], v[242:243] op_sel_hi:[1,0]
	v_pk_mul_f32 v[40:41], v[40:41], v[242:243] op_sel_hi:[1,0]
	v_pk_mul_f32 v[42:43], v[42:43], v[242:243] op_sel_hi:[1,0]
	v_pk_mul_f32 v[44:45], v[44:45], v[242:243] op_sel_hi:[1,0]
	v_pk_mul_f32 v[46:47], v[46:47], v[242:243] op_sel_hi:[1,0]
	v_pk_mul_f32 v[16:17], v[16:17], v[242:243] op_sel_hi:[1,0]
	v_pk_mul_f32 v[18:19], v[18:19], v[242:243] op_sel_hi:[1,0]
	v_pk_mul_f32 v[20:21], v[20:21], v[242:243] op_sel_hi:[1,0]
	v_pk_mul_f32 v[22:23], v[22:23], v[242:243] op_sel_hi:[1,0]
	v_pk_mul_f32 v[24:25], v[24:25], v[242:243] op_sel_hi:[1,0]
	v_pk_mul_f32 v[26:27], v[26:27], v[242:243] op_sel_hi:[1,0]
	v_pk_mul_f32 v[28:29], v[28:29], v[242:243] op_sel_hi:[1,0]
	v_pk_mul_f32 v[30:31], v[30:31], v[242:243] op_sel_hi:[1,0]
	v_pk_mul_f32 v[0:1], v[0:1], v[242:243] op_sel_hi:[1,0]
	v_pk_mul_f32 v[2:3], v[2:3], v[242:243] op_sel_hi:[1,0]
	v_pk_mul_f32 v[4:5], v[4:5], v[242:243] op_sel_hi:[1,0]
	v_pk_mul_f32 v[6:7], v[6:7], v[242:243] op_sel_hi:[1,0]
	v_pk_mul_f32 v[8:9], v[8:9], v[242:243] op_sel_hi:[1,0]
	v_pk_mul_f32 v[10:11], v[10:11], v[242:243] op_sel_hi:[1,0]
	v_pk_mul_f32 v[12:13], v[12:13], v[242:243] op_sel_hi:[1,0]
	v_pk_mul_f32 v[14:15], v[14:15], v[242:243] op_sel_hi:[1,0]
	v_mul_f32_e32 v182, v182, v242
	v_xor_b32_e32 v80, 0x80000000, v183
	v_mov_b32_e32 v81, v80
	v_mov_b32_e32 v82, v80
	v_mov_b32_e32 v83, v80
	v_mov_b32_e32 v84, v80
	v_mov_b32_e32 v85, v80
	v_mov_b32_e32 v86, v80
	v_mov_b32_e32 v87, v80
	v_mov_b32_e32 v88, v80
	v_mov_b32_e32 v89, v80
	v_mov_b32_e32 v90, v80
	v_mov_b32_e32 v91, v80
	v_mov_b32_e32 v92, v80
	v_mov_b32_e32 v93, v80
	v_mov_b32_e32 v94, v80
	v_mov_b32_e32 v95, v80
	s_nop 1
	s_branch .Lmy_d1_res0
.Lmy_d1_rare1:
	s_nop 11
	v_mov_b32_e32 v240, v239
	s_nop 1
	v_permlane32_swap_b32_e32 v239, v240
	v_max_f32_e32 v239, v239, v240
	v_max_f32_e32 v241, 0, v239
	v_exp_f32_e64 v242, -v241
	v_add_f32_e32 v183, v183, v241
	v_sub_f32_e32 v64, v64, v241
	v_sub_f32_e32 v65, v65, v241
	v_sub_f32_e32 v66, v66, v241
	v_sub_f32_e32 v67, v67, v241
	v_sub_f32_e32 v68, v68, v241
	v_sub_f32_e32 v69, v69, v241
	v_sub_f32_e32 v70, v70, v241
	v_sub_f32_e32 v71, v71, v241
	v_sub_f32_e32 v72, v72, v241
	v_sub_f32_e32 v73, v73, v241
	v_sub_f32_e32 v74, v74, v241
	v_sub_f32_e32 v75, v75, v241
	v_sub_f32_e32 v76, v76, v241
	v_sub_f32_e32 v77, v77, v241
	v_sub_f32_e32 v78, v78, v241
	v_sub_f32_e32 v79, v79, v241
	v_pk_mul_f32 v[48:49], v[48:49], v[242:243] op_sel_hi:[1,0]
	v_pk_mul_f32 v[50:51], v[50:51], v[242:243] op_sel_hi:[1,0]
	v_pk_mul_f32 v[52:53], v[52:53], v[242:243] op_sel_hi:[1,0]
	v_pk_mul_f32 v[54:55], v[54:55], v[242:243] op_sel_hi:[1,0]
	v_pk_mul_f32 v[56:57], v[56:57], v[242:243] op_sel_hi:[1,0]
	v_pk_mul_f32 v[58:59], v[58:59], v[242:243] op_sel_hi:[1,0]
	v_pk_mul_f32 v[60:61], v[60:61], v[242:243] op_sel_hi:[1,0]
	v_pk_mul_f32 v[62:63], v[62:63], v[242:243] op_sel_hi:[1,0]
	v_pk_mul_f32 v[32:33], v[32:33], v[242:243] op_sel_hi:[1,0]
	v_pk_mul_f32 v[34:35], v[34:35], v[242:243] op_sel_hi:[1,0]
	v_pk_mul_f32 v[36:37], v[36:37], v[242:243] op_sel_hi:[1,0]
	v_pk_mul_f32 v[38:39], v[38:39], v[242:243] op_sel_hi:[1,0]
	v_pk_mul_f32 v[40:41], v[40:41], v[242:243] op_sel_hi:[1,0]
	v_pk_mul_f32 v[42:43], v[42:43], v[242:243] op_sel_hi:[1,0]
	v_pk_mul_f32 v[44:45], v[44:45], v[242:243] op_sel_hi:[1,0]
	v_pk_mul_f32 v[46:47], v[46:47], v[242:243] op_sel_hi:[1,0]
	v_pk_mul_f32 v[16:17], v[16:17], v[242:243] op_sel_hi:[1,0]
	v_pk_mul_f32 v[18:19], v[18:19], v[242:243] op_sel_hi:[1,0]
	v_pk_mul_f32 v[20:21], v[20:21], v[242:243] op_sel_hi:[1,0]
	v_pk_mul_f32 v[22:23], v[22:23], v[242:243] op_sel_hi:[1,0]
	v_pk_mul_f32 v[24:25], v[24:25], v[242:243] op_sel_hi:[1,0]
	v_pk_mul_f32 v[26:27], v[26:27], v[242:243] op_sel_hi:[1,0]
	v_pk_mul_f32 v[28:29], v[28:29], v[242:243] op_sel_hi:[1,0]
	v_pk_mul_f32 v[30:31], v[30:31], v[242:243] op_sel_hi:[1,0]
	v_pk_mul_f32 v[0:1], v[0:1], v[242:243] op_sel_hi:[1,0]
	v_pk_mul_f32 v[2:3], v[2:3], v[242:243] op_sel_hi:[1,0]
	v_pk_mul_f32 v[4:5], v[4:5], v[242:243] op_sel_hi:[1,0]
	v_pk_mul_f32 v[6:7], v[6:7], v[242:243] op_sel_hi:[1,0]
	v_pk_mul_f32 v[8:9], v[8:9], v[242:243] op_sel_hi:[1,0]
	v_pk_mul_f32 v[10:11], v[10:11], v[242:243] op_sel_hi:[1,0]
	v_pk_mul_f32 v[12:13], v[12:13], v[242:243] op_sel_hi:[1,0]
	v_pk_mul_f32 v[14:15], v[14:15], v[242:243] op_sel_hi:[1,0]
	v_mul_f32_e32 v182, v182, v242
	v_xor_b32_e32 v80, 0x80000000, v183
	v_mov_b32_e32 v81, v80
	v_mov_b32_e32 v82, v80
	v_mov_b32_e32 v83, v80
	v_mov_b32_e32 v84, v80
	v_mov_b32_e32 v85, v80
	v_mov_b32_e32 v86, v80
	v_mov_b32_e32 v87, v80
	v_mov_b32_e32 v88, v80
	v_mov_b32_e32 v89, v80
	v_mov_b32_e32 v90, v80
	v_mov_b32_e32 v91, v80
	v_mov_b32_e32 v92, v80
	v_mov_b32_e32 v93, v80
	v_mov_b32_e32 v94, v80
	v_mov_b32_e32 v95, v80
	s_nop 1
	s_branch .Lmy_d1_res1

; template <int DQK, int DV, bool NA>
; DI void attend(const bf16_t* __restrict__ Q, int q0, const bf16_t* __restrict__ Kb, const bf16_t* __restrict__ Vb,
;                int s0, int n0, int s1, int n1, f32x16 (&o)[DV / 32], char* smem, NAInfo na) {
;     ...
;                     for (int s = 0; s < NS; ++s) kf[s] = *(const bf16x8*)(sK + (sub * 32 + l31) * KS + (s * 16 + hh * 8) * 2);
;                     __builtin_amdgcn_sched_barrier(0);
; #pragma unroll
;                     for (int s = 0; s < NS; ++s) st = mfma32(kf[s], qf[s], st);
;                 }
;                 bf16x8 vf[NDT][2];
; #pragma unroll
;                 for (int d = 0; d < NDT; ++d)
; #pragma unroll
;                     for (int s2 = 0; s2 < 2; ++s2) {
;                         const char* vp = sV + (sub * 32 + 16 * s2 + 4 * hh + q) * VS + (d * 32 + dblk * 16 + 4 * p) * 2;
;                         vf[d][s2] = cat8(tr_read(vp), tr_read(vp + 8 * VS));
;                     }
;                 if (NA && t < n0) {
;                     const float* brow = rpb + (kr - na.qr + 7) * 31 + 15 - qc;
; #pragma unroll
;                     for (int r = 0; r < 16; ++r) {
;                         const int kc = sub * 32 + (r & 3) + 8 * (r >> 2) + 4 * hh;
;                         const bool valid = (kc >= cs) && (kc < cs + 16);
;                         const int bi = valid ? kc : cs;
;                         const float bias = brow[bi];
;                         st[r] = valid ? st[r] + bias : -INFINITY;
;                     }
;                 }
;                 float mx = st[0];
; #pragma unroll
;                 for (int r = 1; r < 16; ++r) mx = fmaxf(mx, st[r]);
;                 mx = xor32_max(mx);
;                 float rsum = 0.f;
;                 if (NA) {
;                     const float mnew = fmaxf(m, mx);
;                     const float muse = (mnew == -INFINITY) ? 0.f : mnew;
;                     const float alpha = __builtin_amdgcn_exp2f(m - muse);
;                     m = mnew;
;                     l *= alpha;
; #pragma unroll
;                     for (int d = 0; d < NDT; ++d)
; #pragma unroll
;                         for (int r = 0; r < 16; ++r) o[d][r] *= alpha;
; #pragma unroll
;                     for (int r = 0; r < 16; ++r) { st[r] = __builtin_amdgcn_exp2f(st[r] - muse); rsum += st[r]; }
;                 } else {
.LBB0_153:
	s_add_i32 s0, s0, 1
	s_and_b32 s1, s0, 1
	s_mul_i32 s2, s1, 0x8400
	v_add_u32_e32 v224, s2, v172
	v_add_u32_e32 v223, s2, v226
	v_add_u32_e32 v224, v224, v222
	v_add_u32_e32 v223, v223, v225
	ds_read_b128 v[140:143], v224
	ds_read_b128 v[144:147], v224 offset:32
	ds_read_b128 v[148:151], v224 offset:64
	ds_read_b128 v[152:155], v224 offset:96
	s_waitcnt lgkmcnt(3)
	v_mfma_f32_32x32x16_bf16 v[96:111], v[140:143], v[120:123], v[80:95]
	ds_read_b128 v[140:143], v224 offset:4608
	s_waitcnt lgkmcnt(3)
	v_mfma_f32_32x32x16_bf16 v[96:111], v[144:147], v[124:127], v[96:111]
	ds_read_b128 v[144:147], v224 offset:4640
	s_waitcnt lgkmcnt(3)
	v_mfma_f32_32x32x16_bf16 v[96:111], v[148:151], v[116:119], v[96:111]
	ds_read_b128 v[148:151], v224 offset:4672
	s_waitcnt lgkmcnt(3)
	v_mfma_f32_32x32x16_bf16 v[96:111], v[152:155], v[112:115], v[96:111]
	ds_read_b128 v[152:155], v224 offset:4704
	ds_read_b64_tr_b16 v[156:157], v223 offset:9216
	ds_read_b64_tr_b16 v[158:159], v223 offset:11776
	ds_read_b64_tr_b16 v[160:161], v223 offset:9280
	ds_read_b64_tr_b16 v[162:163], v223 offset:11840
	ds_read_b64_tr_b16 v[164:165], v223 offset:9344
	ds_read_b64_tr_b16 v[166:167], v223 offset:11904
	ds_read_b64_tr_b16 v[168:169], v223 offset:9408
	ds_read_b64_tr_b16 v[170:171], v223 offset:11968
	s_nop 2
	v_max3_f32 v239, v96, v97, v98
	v_max3_f32 v240, v104, v105, v106
	v_max3_f32 v239, v239, v99, v100
	v_max3_f32 v240, v240, v107, v108
	v_max3_f32 v239, v239, v101, v102
	v_max3_f32 v240, v240, v109, v110
	v_max3_f32 v239, v239, v103, v111
	v_max_f32_e32 v239, v239, v240
	v_cmp_lt_f32_e32 vcc, 0x41000000, v239
	s_cbranch_vccnz .Lmy_d2_rare0
.Lmy_d2_res0:
	s_waitcnt lgkmcnt(11)
	v_mfma_f32_32x32x16_bf16 v[64:79], v[140:143], v[120:123], v[80:95]
	v_exp_f32_e32 v96, v96
	v_exp_f32_e32 v97, v97
	v_exp_f32_e32 v98, v98
	v_exp_f32_e32 v99, v99
	v_exp_f32_e32 v100, v100
	v_exp_f32_e32 v101, v101
	v_exp_f32_e32 v102, v102
	v_exp_f32_e32 v103, v103
	v_add_f32_e32 v244, v96, v97
	v_add_f32_e32 v244, v244, v98
	s_waitcnt lgkmcnt(10)
	v_mfma_f32_32x32x16_bf16 v[64:79], v[144:147], v[124:127], v[64:79]
	v_add_f32_e32 v244, v244, v99
	v_add_f32_e32 v244, v244, v100
	v_add_f32_e32 v244, v244, v101
	v_add_f32_e32 v244, v244, v102
	v_add_f32_e32 v244, v244, v103
	v_cvt_pk_bf16_f32 v96, v96, v97
	v_cvt_pk_bf16_f32 v97, v98, v99
	v_cvt_pk_bf16_f32 v98, v100, v101
	v_cvt_pk_bf16_f32 v99, v102, v103
	v_exp_f32_e32 v104, v104
	s_waitcnt lgkmcnt(9)
	v_mfma_f32_32x32x16_bf16 v[64:79], v[148:151], v[116:119], v[64:79]
	v_exp_f32_e32 v105, v105
	v_exp_f32_e32 v106, v106
	v_exp_f32_e32 v107, v107
	v_exp_f32_e32 v108, v108
	v_exp_f32_e32 v109, v109
	v_exp_f32_e32 v110, v110
	v_exp_f32_e32 v111, v111
	v_add_f32_e32 v245, v104, v105
	v_add_f32_e32 v245, v245, v106
	s_waitcnt lgkmcnt(8)
	v_mfma_f32_32x32x16_bf16 v[64:79], v[152:155], v[112:115], v[64:79]
	v_add_f32_e32 v245, v245, v107
	v_add_f32_e32 v245, v245, v108
	v_add_f32_e32 v245, v245, v109
	v_add_f32_e32 v245, v245, v110
	v_add_f32_e32 v245, v245, v111
	v_cvt_pk_bf16_f32 v104, v104, v105
	v_cvt_pk_bf16_f32 v105, v106, v107
	v_cvt_pk_bf16_f32 v106, v108, v109
	v_cvt_pk_bf16_f32 v107, v110, v111
	ds_read_b64_tr_b16 v[140:141], v223 offset:14336
	ds_read_b64_tr_b16 v[142:143], v223 offset:16896
	ds_read_b64_tr_b16 v[144:145], v223 offset:14400
	ds_read_b64_tr_b16 v[146:147], v223 offset:16960
	ds_read_b64_tr_b16 v[148:149], v223 offset:14464
	ds_read_b64_tr_b16 v[150:151], v223 offset:17024
	ds_read_b64_tr_b16 v[152:153], v223 offset:14528
	ds_read_b64_tr_b16 v[154:155], v223 offset:17088
	s_waitcnt lgkmcnt(8)
	v_mfma_f32_32x32x16_bf16 v[48:63], v[156:159], v[96:99], v[48:63]
	ds_read_b64_tr_b16 v[156:157], v223 offset:19456
	ds_read_b64_tr_b16 v[158:159], v223 offset:22016
	v_mfma_f32_32x32x16_bf16 v[32:47], v[160:163], v[96:99], v[32:47]
	ds_read_b64_tr_b16 v[160:161], v223 offset:19520
	ds_read_b64_tr_b16 v[162:163], v223 offset:22080
	v_max3_f32 v239, v64, v65, v66
	v_max3_f32 v240, v72, v73, v74
	v_mfma_f32_32x32x16_bf16 v[16:31], v[164:167], v[96:99], v[16:31]
	ds_read_b64_tr_b16 v[164:165], v223 offset:19584
	ds_read_b64_tr_b16 v[166:167], v223 offset:22144
	v_max3_f32 v239, v239, v67, v68
	v_mfma_f32_32x32x16_bf16 v[0:15], v[168:171], v[96:99], v[0:15]
	ds_read_b64_tr_b16 v[168:169], v223 offset:19648
	ds_read_b64_tr_b16 v[170:171], v223 offset:22208
	v_max3_f32 v240, v240, v75, v76
	s_waitcnt lgkmcnt(8)
	v_mfma_f32_32x32x16_bf16 v[48:63], v[140:143], v[104:107], v[48:63]
	ds_read_b64_tr_b16 v[140:141], v223 offset:24576
	ds_read_b64_tr_b16 v[142:143], v223 offset:27136
	v_max3_f32 v239, v239, v69, v70
	v_mfma_f32_32x32x16_bf16 v[32:47], v[144:147], v[104:107], v[32:47]
	ds_read_b64_tr_b16 v[144:145], v223 offset:24640
	ds_read_b64_tr_b16 v[146:147], v223 offset:27200
	v_max3_f32 v240, v240, v77, v78
	v_mfma_f32_32x32x16_bf16 v[16:31], v[148:151], v[104:107], v[16:31]
	ds_read_b64_tr_b16 v[148:149], v223 offset:24704
	ds_read_b64_tr_b16 v[150:151], v223 offset:27264
	v_max3_f32 v239, v239, v71, v79
	v_mfma_f32_32x32x16_bf16 v[0:15], v[152:155], v[104:107], v[0:15]
	ds_read_b64_tr_b16 v[152:153], v223 offset:24768
	ds_read_b64_tr_b16 v[154:155], v223 offset:27328
	v_max_f32_e32 v239, v239, v240
	v_cmp_lt_f32_e32 vcc, 0x41000000, v239
	s_cbranch_vccnz .Lmy_d2_rare1

; template <int DQK, int DV, bool NA>
; DI void attend(const bf16_t* __restrict__ Q, int q0, const bf16_t* __restrict__ Kb, const bf16_t* __restrict__ Vb,
;                int s0, int n0, int s1, int n1, f32x16 (&o)[DV / 32], char* smem, NAInfo na) {
;     ...
;                     const bool first = (t == 0) && (sub == 0);
;                     if (first || __builtin_amdgcn_ballot_w64(mx > 8.f) != 0) {
;                         const float delta = first ? mx : fmaxf(mx, 0.f);
;                         const float alpha = first ? 1.f : __builtin_amdgcn_exp2f(-delta);
;                         m += delta;
;                         l *= alpha;
; #pragma unroll
;                         for (int d = 0; d < NDT; ++d)
; #pragma unroll
;                             for (int r = 0; r < 16; ++r) o[d][r] *= alpha;
; #pragma unroll
;                         for (int r = 0; r < 16; ++r) { st[r] -= delta; cinit[r] = -m; }
;                     }
.Lmy_d2_rare0:
	v_mov_b32_e32 v240, v239
	s_nop 1
	v_permlane32_swap_b32_e32 v239, v240
	v_max_f32_e32 v239, v239, v240
	v_max_f32_e32 v241, 0, v239
	v_exp_f32_e64 v242, -v241
	v_add_f32_e32 v189, v189, v241
	v_sub_f32_e32 v96, v96, v241
	v_sub_f32_e32 v97, v97, v241
	v_sub_f32_e32 v98, v98, v241
	v_sub_f32_e32 v99, v99, v241
	v_sub_f32_e32 v100, v100, v241
	v_sub_f32_e32 v101, v101, v241
	v_sub_f32_e32 v102, v102, v241
	v_sub_f32_e32 v103, v103, v241
	v_sub_f32_e32 v104, v104, v241
	v_sub_f32_e32 v105, v105, v241
	v_sub_f32_e32 v106, v106, v241
	v_sub_f32_e32 v107, v107, v241
	v_sub_f32_e32 v108, v108, v241
	v_sub_f32_e32 v109, v109, v241
	v_sub_f32_e32 v110, v110, v241
	v_sub_f32_e32 v111, v111, v241
	v_pk_mul_f32 v[48:49], v[48:49], v[242:243] op_sel_hi:[1,0]
	v_pk_mul_f32 v[50:51], v[50:51], v[242:243] op_sel_hi:[1,0]
	v_pk_mul_f32 v[52:53], v[52:53], v[242:243] op_sel_hi:[1,0]
	v_pk_mul_f32 v[54:55], v[54:55], v[242:243] op_sel_hi:[1,0]
	v_pk_mul_f32 v[56:57], v[56:57], v[242:243] op_sel_hi:[1,0]
	v_pk_mul_f32 v[58:59], v[58:59], v[242:243] op_sel_hi:[1,0]
	v_pk_mul_f32 v[60:61], v[60:61], v[242:243] op_sel_hi:[1,0]
	v_pk_mul_f32 v[62:63], v[62:63], v[242:243] op_sel_hi:[1,0]
	v_pk_mul_f32 v[32:33], v[32:33], v[242:243] op_sel_hi:[1,0]
	v_pk_mul_f32 v[34:35], v[34:35], v[242:243] op_sel_hi:[1,0]
	v_pk_mul_f32 v[36:37], v[36:37], v[242:243] op_sel_hi:[1,0]
	v_pk_mul_f32 v[38:39], v[38:39], v[242:243] op_sel_hi:[1,0]
	v_pk_mul_f32 v[40:41], v[40:41], v[242:243] op_sel_hi:[1,0]
	v_pk_mul_f32 v[42:43], v[42:43], v[242:243] op_sel_hi:[1,0]
	v_pk_mul_f32 v[44:45], v[44:45], v[242:243] op_sel_hi:[1,0]
	v_pk_mul_f32 v[46:47], v[46:47], v[242:243] op_sel_hi:[1,0]
	v_pk_mul_f32 v[16:17], v[16:17], v[242:243] op_sel_hi:[1,0]
	v_pk_mul_f32 v[18:19], v[18:19], v[242:243] op_sel_hi:[1,0]
	v_pk_mul_f32 v[20:21], v[20:21], v[242:243] op_sel_hi:[1,0]
	v_pk_mul_f32 v[22:23], v[22:23], v[242:243] op_sel_hi:[1,0]
	v_pk_mul_f32 v[24:25], v[24:25], v[242:243] op_sel_hi:[1,0]
	v_pk_mul_f32 v[26:27], v[26:27], v[242:243] op_sel_hi:[1,0]
	v_pk_mul_f32 v[28:29], v[28:29], v[242:243] op_sel_hi:[1,0]
	v_pk_mul_f32 v[30:31], v[30:31], v[242:243] op_sel_hi:[1,0]
	v_pk_mul_f32 v[0:1], v[0:1], v[242:243] op_sel_hi:[1,0]
	v_pk_mul_f32 v[2:3], v[2:3], v[242:243] op_sel_hi:[1,0]
	v_pk_mul_f32 v[4:5], v[4:5], v[242:243] op_sel_hi:[1,0]
	v_pk_mul_f32 v[6:7], v[6:7], v[242:243] op_sel_hi:[1,0]
	v_pk_mul_f32 v[8:9], v[8:9], v[242:243] op_sel_hi:[1,0]
	v_pk_mul_f32 v[10:11], v[10:11], v[242:243] op_sel_hi:[1,0]
	v_pk_mul_f32 v[12:13], v[12:13], v[242:243] op_sel_hi:[1,0]
	v_pk_mul_f32 v[14:15], v[14:15], v[242:243] op_sel_hi:[1,0]
	v_mul_f32_e32 v188, v188, v242
	v_xor_b32_e32 v80, 0x80000000, v189
	v_mov_b32_e32 v81, v80
	v_mov_b32_e32 v82, v80
	v_mov_b32_e32 v83, v80
	v_mov_b32_e32 v84, v80
	v_mov_b32_e32 v85, v80
	v_mov_b32_e32 v86, v80
	v_mov_b32_e32 v87, v80
	v_mov_b32_e32 v88, v80
	v_mov_b32_e32 v89, v80
	v_mov_b32_e32 v90, v80
	v_mov_b32_e32 v91, v80
	v_mov_b32_e32 v92, v80
	v_mov_b32_e32 v93, v80
	v_mov_b32_e32 v94, v80
	v_mov_b32_e32 v95, v80
	s_nop 1
	s_branch .Lmy_d2_res0
.Lmy_d2_rare1:
	s_nop 11
	v_mov_b32_e32 v240, v239
	s_nop 1
	v_permlane32_swap_b32_e32 v239, v240
	v_max_f32_e32 v239, v239, v240
	v_max_f32_e32 v241, 0, v239
	v_exp_f32_e64 v242, -v241
	v_add_f32_e32 v189, v189, v241
	v_sub_f32_e32 v64, v64, v241
	v_sub_f32_e32 v65, v65, v241
	v_sub_f32_e32 v66, v66, v241
	v_sub_f32_e32 v67, v67, v241
	v_sub_f32_e32 v68, v68, v241
	v_sub_f32_e32 v69, v69, v241
	v_sub_f32_e32 v70, v70, v241
	v_sub_f32_e32 v71, v71, v241
	v_sub_f32_e32 v72, v72, v241
	v_sub_f32_e32 v73, v73, v241
	v_sub_f32_e32 v74, v74, v241
	v_sub_f32_e32 v75, v75, v241
	v_sub_f32_e32 v76, v76, v241
	v_sub_f32_e32 v77, v77, v241
	v_sub_f32_e32 v78, v78, v241
	v_sub_f32_e32 v79, v79, v241
	v_pk_mul_f32 v[48:49], v[48:49], v[242:243] op_sel_hi:[1,0]
	v_pk_mul_f32 v[50:51], v[50:51], v[242:243] op_sel_hi:[1,0]
	v_pk_mul_f32 v[52:53], v[52:53], v[242:243] op_sel_hi:[1,0]
	v_pk_mul_f32 v[54:55], v[54:55], v[242:243] op_sel_hi:[1,0]
	v_pk_mul_f32 v[56:57], v[56:57], v[242:243] op_sel_hi:[1,0]
	v_pk_mul_f32 v[58:59], v[58:59], v[242:243] op_sel_hi:[1,0]
	v_pk_mul_f32 v[60:61], v[60:61], v[242:243] op_sel_hi:[1,0]
	v_pk_mul_f32 v[62:63], v[62:63], v[242:243] op_sel_hi:[1,0]
	v_pk_mul_f32 v[32:33], v[32:33], v[242:243] op_sel_hi:[1,0]
	v_pk_mul_f32 v[34:35], v[34:35], v[242:243] op_sel_hi:[1,0]
	v_pk_mul_f32 v[36:37], v[36:37], v[242:243] op_sel_hi:[1,0]
	v_pk_mul_f32 v[38:39], v[38:39], v[242:243] op_sel_hi:[1,0]
	v_pk_mul_f32 v[40:41], v[40:41], v[242:243] op_sel_hi:[1,0]
	v_pk_mul_f32 v[42:43], v[42:43], v[242:243] op_sel_hi:[1,0]
	v_pk_mul_f32 v[44:45], v[44:45], v[242:243] op_sel_hi:[1,0]
	v_pk_mul_f32 v[46:47], v[46:47], v[242:243] op_sel_hi:[1,0]
	v_pk_mul_f32 v[16:17], v[16:17], v[242:243] op_sel_hi:[1,0]
	v_pk_mul_f32 v[18:19], v[18:19], v[242:243] op_sel_hi:[1,0]
	v_pk_mul_f32 v[20:21], v[20:21], v[242:243] op_sel_hi:[1,0]
	v_pk_mul_f32 v[22:23], v[22:23], v[242:243] op_sel_hi:[1,0]
	v_pk_mul_f32 v[24:25], v[24:25], v[242:243] op_sel_hi:[1,0]
	v_pk_mul_f32 v[26:27], v[26:27], v[242:243] op_sel_hi:[1,0]
	v_pk_mul_f32 v[28:29], v[28:29], v[242:243] op_sel_hi:[1,0]
	v_pk_mul_f32 v[30:31], v[30:31], v[242:243] op_sel_hi:[1,0]
	v_pk_mul_f32 v[0:1], v[0:1], v[242:243] op_sel_hi:[1,0]
	v_pk_mul_f32 v[2:3], v[2:3], v[242:243] op_sel_hi:[1,0]
	v_pk_mul_f32 v[4:5], v[4:5], v[242:243] op_sel_hi:[1,0]
	v_pk_mul_f32 v[6:7], v[6:7], v[242:243] op_sel_hi:[1,0]
	v_pk_mul_f32 v[8:9], v[8:9], v[242:243] op_sel_hi:[1,0]
	v_pk_mul_f32 v[10:11], v[10:11], v[242:243] op_sel_hi:[1,0]
	v_pk_mul_f32 v[12:13], v[12:13], v[242:243] op_sel_hi:[1,0]
	v_pk_mul_f32 v[14:15], v[14:15], v[242:243] op_sel_hi:[1,0]
	v_mul_f32_e32 v188, v188, v242
	v_xor_b32_e32 v80, 0x80000000, v189
	v_mov_b32_e32 v81, v80
	v_mov_b32_e32 v82, v80
	v_mov_b32_e32 v83, v80
	v_mov_b32_e32 v84, v80
	v_mov_b32_e32 v85, v80
	v_mov_b32_e32 v86, v80
	v_mov_b32_e32 v87, v80
	v_mov_b32_e32 v88, v80
	v_mov_b32_e32 v89, v80
	v_mov_b32_e32 v90, v80
	v_mov_b32_e32 v91, v80
	v_mov_b32_e32 v92, v80
	v_mov_b32_e32 v93, v80
	v_mov_b32_e32 v94, v80
	v_mov_b32_e32 v95, v80
	s_nop 1
	s_branch .Lmy_d2_res1

; DI f32x16 mfma32(bf16x8 a, bf16x8 b, f32x16 c) { return __builtin_amdgcn_mfma_f32_32x32x16_bf16(a, b, c, 0, 0, 0); }
; DI s16x4 tr_read(const char* p) { bfx4 r = __builtin_amdgcn_ds_read_tr16_b64_v4bf16((LDS_AS bfx4*)p); return __builtin_bit_cast(s16x4, r); }
; DI bf16x8 cat8(s16x4 lo, s16x4 hi) { return __builtin_shufflevector(lo, hi, 0, 1, 2, 3, 4, 5, 6, 7); }
; template <int BM, class Epi>
; DI void gemm_tile(const bf16_t* __restrict__ A, int lda, const bf16_t* __restrict__ B, int ldb, int K, int row0, int col0, const Epi& epi, char* smem) {
;     ...
;     for (int kt = 0; kt < nk; ++kt) {
;         const char* cur = smem + (kt & 1) * GSTAGE;
;         char* nxt = smem + ((kt & 1) ^ 1) * GSTAGE;
;         const bool w1 = kt + 1 < nk, l2 = kt + 2 < nk;
;         const bf16_t* a2 = ag + (size_t)(kt + 2) * 64; const bf16_t* b2 = bg + (size_t)(kt + 2) * 64 * ldb;
; #pragma unroll
;         for (int s = 0; s < 4; ++s) {
;             bf16x8 xf[MI], wf[2];
; #pragma unroll
;             for (int mi = 0; mi < MI; ++mi) xf[mi] = *(const bf16x8*)(cur + xoff + mi * 32 * GA_S + s * 32);
; #pragma unroll
;             for (int ni = 0; ni < 2; ++ni) {
;                 const char* wp = cur + woff + s * 16 * GB_S + ni * 64;
;                 wf[ni] = cat8(tr_read(wp), tr_read(wp + 4 * GB_S));
;             }
; #pragma unroll
;             for (int mi = 0; mi < MI; ++mi)
; #pragma unroll
;                 for (int ni = 0; ni < 2; ++ni) acc[mi][ni] = mfma32(wf[ni], xf[mi], acc[mi][ni]);
;             if (w1) {
;                 if (s < NA_) *(u32x4*)(nxt + aw + 64 * s * GA_S) = ra[s];
;                 *(u32x4*)(nxt + bw + 16 * s * GB_S) = rb[s];
;             }
;             if (l2) {
;                 if (s < NA_) ra[s] = *(const u32x4*)(a2 + (size_t)(64 * s) * lda);
;                 rb[s] = *(const u32x4*)(b2 + (size_t)(16 * s) * ldb);
;             }
;         }
;         __syncthreads();
;     }
.LBB0_1487:
	s_and_b32 s0, s11, 1
	s_mul_i32 s1, s0, 0x12000
	v_add3_u32 v172, s1, v180, v181
	v_add3_u32 v165, s1, v167, v179
	ds_read_b64_tr_b16 v[234:235], v172 offset:36864
	ds_read_b64_tr_b16 v[236:237], v172 offset:39168
	ds_read_b128 v[184:187], v165
	ds_read_b64_tr_b16 v[238:239], v172 offset:36928
	ds_read_b64_tr_b16 v[240:241], v172 offset:39232
	ds_read_b128 v[188:191], v165 offset:4608
	ds_read_b128 v[218:221], v165 offset:9216
	ds_read_b128 v[222:225], v165 offset:13824
	s_xor_b32 s0, s0, 1
	s_mul_i32 s0, s0, 0x12000
	v_add_u32_e32 v233, 0x9000, v172
	v_add_u32_e32 v217, s0, v166
	v_add_u32_e32 v232, s0, v183
	s_add_i32 s11, s11, 1
	s_waitcnt lgkmcnt(5)
	v_mfma_f32_32x32x16_bf16 v[112:127], v[234:237], v[184:187], v[112:127]
	ds_read_b64_tr_b16 v[242:243], v172 offset:46080
	ds_read_b64_tr_b16 v[244:245], v172 offset:48384
	ds_read_b64_tr_b16 v[246:247], v172 offset:46144
	ds_read_b64_tr_b16 v[248:249], v172 offset:48448
	s_waitcnt lgkmcnt(7)
	v_mfma_f32_32x32x16_bf16 v[96:111], v[238:241], v[184:187], v[96:111]
	ds_read_b128 v[184:187], v165 offset:32
	s_waitcnt lgkmcnt(7)
	v_mfma_f32_32x32x16_bf16 v[80:95], v[234:237], v[188:191], v[80:95]
	v_mfma_f32_32x32x16_bf16 v[64:79], v[238:241], v[188:191], v[64:79]
	ds_read_b128 v[188:191], v165 offset:4640
	s_waitcnt vmcnt(7)
	ds_write_b128 v217, v[152:155]
	s_waitcnt vmcnt(3)
	ds_write_b128 v232, v[156:159] offset:36864
	s_waitcnt lgkmcnt(9)
	v_mfma_f32_32x32x16_bf16 v[48:63], v[234:237], v[218:221], v[48:63]
	v_mfma_f32_32x32x16_bf16 v[32:47], v[238:241], v[218:221], v[32:47]
	ds_read_b128 v[218:221], v165 offset:9248
	s_waitcnt lgkmcnt(9)
	v_mfma_f32_32x32x16_bf16 v[16:31], v[234:237], v[222:225], v[16:31]
	v_mfma_f32_32x32x16_bf16 v[0:15], v[238:241], v[222:225], v[0:15]
	ds_read_b128 v[222:225], v165 offset:13856
	s_waitcnt lgkmcnt(5)
	v_mfma_f32_32x32x16_bf16 v[112:127], v[242:245], v[184:187], v[112:127]
	ds_read_b64_tr_b16 v[234:235], v172 offset:55296
	ds_read_b64_tr_b16 v[236:237], v172 offset:57600
	ds_read_b64_tr_b16 v[238:239], v172 offset:55360
	ds_read_b64_tr_b16 v[240:241], v172 offset:57664
	v_mfma_f32_32x32x16_bf16 v[96:111], v[246:249], v[184:187], v[96:111]
	ds_read_b128 v[184:187], v165 offset:64
	s_waitcnt lgkmcnt(9)
	v_mfma_f32_32x32x16_bf16 v[80:95], v[242:245], v[188:191], v[80:95]
	v_mfma_f32_32x32x16_bf16 v[64:79], v[246:249], v[188:191], v[64:79]
	ds_read_b128 v[188:191], v165 offset:4672
	ds_write_b128 v217, v[144:147] offset:9216
	s_waitcnt vmcnt(2)
	ds_write_b128 v232, v[148:151] offset:46080
	s_waitcnt lgkmcnt(9)
	v_mfma_f32_32x32x16_bf16 v[48:63], v[242:245], v[218:221], v[48:63]
	v_mfma_f32_32x32x16_bf16 v[32:47], v[246:249], v[218:221], v[32:47]
	ds_read_b128 v[218:221], v165 offset:9280
	s_waitcnt lgkmcnt(9)
	v_mfma_f32_32x32x16_bf16 v[16:31], v[242:245], v[222:225], v[16:31]
	v_mfma_f32_32x32x16_bf16 v[0:15], v[246:249], v[222:225], v[0:15]
	ds_read_b128 v[222:225], v165 offset:13888
	s_waitcnt lgkmcnt(5)
	v_mfma_f32_32x32x16_bf16 v[112:127], v[234:237], v[184:187], v[112:127]
	ds_read_b64_tr_b16 v[242:243], v172 offset:64512
	ds_read_b64_tr_b16 v[244:245], v233 offset:29952
	ds_read_b64_tr_b16 v[246:247], v172 offset:64576
	ds_read_b64_tr_b16 v[248:249], v233 offset:30016
	v_mfma_f32_32x32x16_bf16 v[96:111], v[238:241], v[184:187], v[96:111]
	ds_read_b128 v[184:187], v165 offset:96
	s_waitcnt lgkmcnt(9)
	v_mfma_f32_32x32x16_bf16 v[80:95], v[234:237], v[188:191], v[80:95]
	v_mfma_f32_32x32x16_bf16 v[64:79], v[238:241], v[188:191], v[64:79]
	ds_read_b128 v[188:191], v165 offset:4704
	ds_write_b128 v217, v[136:139] offset:18432
	s_waitcnt vmcnt(1)
	ds_write_b128 v232, v[140:143] offset:55296
	s_waitcnt lgkmcnt(9)
	v_mfma_f32_32x32x16_bf16 v[48:63], v[234:237], v[218:221], v[48:63]
	v_mfma_f32_32x32x16_bf16 v[32:47], v[238:241], v[218:221], v[32:47]
	ds_read_b128 v[218:221], v165 offset:9312
	v_add_u32_e32 v192, s17, v168
	v_add_u32_e32 v193, s18, v170
	v_add_u32_e32 v226, s19, v168
	v_add_u32_e32 v227, s20, v170
	v_add_u32_e32 v228, s21, v168
	v_add_u32_e32 v229, s22, v170
	v_add_u32_e32 v230, s23, v168
	v_add_u32_e32 v231, s24, v170
	v_lshl_add_u64 v[170:171], v[170:171], 0, s[28:29]
	v_lshl_add_u64 v[168:169], v[168:169], 0, s[26:27]
	s_waitcnt lgkmcnt(9)
	v_mfma_f32_32x32x16_bf16 v[16:31], v[234:237], v[222:225], v[16:31]
	v_mfma_f32_32x32x16_bf16 v[0:15], v[238:241], v[222:225], v[0:15]
	ds_read_b128 v[222:225], v165 offset:13920
	s_waitcnt lgkmcnt(5)
	v_mfma_f32_32x32x16_bf16 v[112:127], v[242:245], v[184:187], v[112:127]
	v_mfma_f32_32x32x16_bf16 v[96:111], v[246:249], v[184:187], v[96:111]
	global_load_dwordx4 v[152:155], v192, s[94:95] offset:768
	global_load_dwordx4 v[156:159], v193, s[94:95]
	s_waitcnt lgkmcnt(4)
	v_mfma_f32_32x32x16_bf16 v[80:95], v[242:245], v[188:191], v[80:95]
	v_mfma_f32_32x32x16_bf16 v[64:79], v[246:249], v[188:191], v[64:79]
	global_load_dwordx4 v[144:147], v226, s[94:95] offset:768
	global_load_dwordx4 v[148:151], v227, s[94:95]
	global_load_dwordx4 v[136:139], v228, s[94:95] offset:768
	global_load_dwordx4 v[140:143], v229, s[94:95]
	s_waitcnt lgkmcnt(1)
	v_mfma_f32_32x32x16_bf16 v[48:63], v[242:245], v[218:221], v[48:63]
	v_mfma_f32_32x32x16_bf16 v[32:47], v[246:249], v[218:221], v[32:47]
	ds_write_b128 v217, v[128:131] offset:27648
	s_waitcnt vmcnt(6)
	ds_write_b128 v232, v[132:135] offset:64512
	global_load_dwordx4 v[128:131], v230, s[94:95] offset:768
	global_load_dwordx4 v[132:135], v231, s[94:95]
	s_waitcnt lgkmcnt(2)
	v_mfma_f32_32x32x16_bf16 v[16:31], v[242:245], v[222:225], v[16:31]
	v_mfma_f32_32x32x16_bf16 v[0:15], v[246:249], v[222:225], v[0:15]
	s_cmp_eq_u32 s11, 42
	s_waitcnt lgkmcnt(0)
	s_barrier
; DI f32x16 mfma32(bf16x8 a, bf16x8 b, f32x16 c) { return __builtin_amdgcn_mfma_f32_32x32x16_bf16(a, b, c, 0, 0, 0); }
; DI s16x4 tr_read(const char* p) { bfx4 r = __builtin_amdgcn_ds_read_tr16_b64_v4bf16((LDS_AS bfx4*)p); return __builtin_bit_cast(s16x4, r); }
; DI bf16x8 cat8(s16x4 lo, s16x4 hi) { return __builtin_shufflevector(lo, hi, 0, 1, 2, 3, 4, 5, 6, 7); }
; template <int BM, class Epi>
; DI void gemm_tile(const bf16_t* __restrict__ A, int lda, const bf16_t* __restrict__ B, int ldb, int K, int row0, int col0, const Epi& epi, char* smem) {
;     ...
;     for (int kt = 0; kt < nk; ++kt) {
;         const char* cur = smem + (kt & 1) * GSTAGE;
;         char* nxt = smem + ((kt & 1) ^ 1) * GSTAGE;
;         const bool w1 = kt + 1 < nk, l2 = kt + 2 < nk;
;         const bf16_t* a2 = ag + (size_t)(kt + 2) * 64; const bf16_t* b2 = bg + (size_t)(kt + 2) * 64 * ldb;
; #pragma unroll
;         for (int s = 0; s < 4; ++s) {
;             bf16x8 xf[MI], wf[2];
; #pragma unroll
;             for (int mi = 0; mi < MI; ++mi) xf[mi] = *(const bf16x8*)(cur + xoff + mi * 32 * GA_S + s * 32);
; #pragma unroll
;             for (int ni = 0; ni < 2; ++ni) {
;                 const char* wp = cur + woff + s * 16 * GB_S + ni * 64;
;                 wf[ni] = cat8(tr_read(wp), tr_read(wp + 4 * GB_S));
;             }
; #pragma unroll
;             for (int mi = 0; mi < MI; ++mi)
; #pragma unroll
;                 for (int ni = 0; ni < 2; ++ni) acc[mi][ni] = mfma32(wf[ni], xf[mi], acc[mi][ni]);
;             if (w1) {
;                 if (s < NA_) *(u32x4*)(nxt + aw + 64 * s * GA_S) = ra[s];
;                 *(u32x4*)(nxt + bw + 16 * s * GB_S) = rb[s];
;             }
;             if (l2) {
;                 if (s < NA_) ra[s] = *(const u32x4*)(a2 + (size_t)(64 * s) * lda);
;                 rb[s] = *(const u32x4*)(b2 + (size_t)(16 * s) * ldb);
;             }
;         }
;         __syncthreads();
;     }
	s_cbranch_scc0 .LBB0_1487
	s_add_i32 s0, 0, 0x12000
	v_add3_u32 v165, 0, v167, v179
	v_add3_u32 v164, v182, v164, s0
	v_add3_u32 v172, 0, v180, v181
	ds_read_b128 v[168:171], v165
	ds_read_b128 v[182:185], v165 offset:4608
	ds_read_b128 v[186:189], v165 offset:9216
	ds_read_b128 v[190:193], v165 offset:13824
	ds_read_b64_tr_b16 v[218:219], v172 offset:36864
	ds_read_b64_tr_b16 v[220:221], v172 offset:39168
	ds_read_b64_tr_b16 v[222:223], v172 offset:36928
	ds_read_b64_tr_b16 v[224:225], v172 offset:39232
	s_waitcnt lgkmcnt(2)
	v_mfma_f32_32x32x16_bf16 v[112:127], v[218:221], v[168:171], v[112:127]
	v_add_u32_e32 v166, s0, v166
	s_waitcnt vmcnt(7)
	ds_write_b128 v166, v[152:155]
	s_waitcnt vmcnt(6)
	ds_write_b128 v164, v[156:159] offset:36864
	v_add_u32_e32 v217, 0x9000, v172
	s_add_i32 s3, s3, s15
	s_cmp_gt_i32 s3, 63
	s_waitcnt lgkmcnt(2)
	v_mfma_f32_32x32x16_bf16 v[96:111], v[222:225], v[168:171], v[96:111]
	v_mfma_f32_32x32x16_bf16 v[48:63], v[218:221], v[186:189], v[48:63]
	v_mfma_f32_32x32x16_bf16 v[32:47], v[222:225], v[186:189], v[32:47]
	v_mfma_f32_32x32x16_bf16 v[80:95], v[218:221], v[182:185], v[80:95]
	v_mfma_f32_32x32x16_bf16 v[64:79], v[222:225], v[182:185], v[64:79]
	v_mfma_f32_32x32x16_bf16 v[16:31], v[218:221], v[190:193], v[16:31]
	v_mfma_f32_32x32x16_bf16 v[0:15], v[222:225], v[190:193], v[0:15]
	ds_read_b128 v[152:155], v165 offset:32
	ds_read_b128 v[156:159], v165 offset:4640
	ds_read_b128 v[168:171], v165 offset:9248
	ds_read_b128 v[182:185], v165 offset:13856
	ds_read_b64_tr_b16 v[186:187], v172 offset:46080
	ds_read_b64_tr_b16 v[188:189], v172 offset:48384
	ds_read_b64_tr_b16 v[190:191], v172 offset:46144
	ds_read_b64_tr_b16 v[192:193], v172 offset:48448
	s_waitcnt vmcnt(5)
	ds_write_b128 v166, v[144:147] offset:9216
	s_waitcnt vmcnt(4)
	ds_write_b128 v164, v[148:151] offset:46080
	s_waitcnt lgkmcnt(4)
	v_mfma_f32_32x32x16_bf16 v[112:127], v[186:189], v[152:155], v[112:127]
	s_waitcnt lgkmcnt(2)
	v_mfma_f32_32x32x16_bf16 v[96:111], v[190:193], v[152:155], v[96:111]
	v_mfma_f32_32x32x16_bf16 v[48:63], v[186:189], v[168:171], v[48:63]
	v_mfma_f32_32x32x16_bf16 v[32:47], v[190:193], v[168:171], v[32:47]
	v_mfma_f32_32x32x16_bf16 v[80:95], v[186:189], v[156:159], v[80:95]
	v_mfma_f32_32x32x16_bf16 v[64:79], v[190:193], v[156:159], v[64:79]
	v_mfma_f32_32x32x16_bf16 v[16:31], v[186:189], v[182:185], v[16:31]
	v_mfma_f32_32x32x16_bf16 v[0:15], v[190:193], v[182:185], v[0:15]
	ds_read_b128 v[144:147], v165 offset:64
	ds_read_b128 v[148:151], v165 offset:4672
	ds_read_b128 v[152:155], v165 offset:9280
	ds_read_b128 v[156:159], v165 offset:13888
	ds_read_b64_tr_b16 v[168:169], v172 offset:55296
	ds_read_b64_tr_b16 v[170:171], v172 offset:57600
	ds_read_b64_tr_b16 v[182:183], v172 offset:55360
	ds_read_b64_tr_b16 v[184:185], v172 offset:57664
	s_waitcnt vmcnt(3)
	ds_write_b128 v166, v[136:139] offset:18432
	s_waitcnt vmcnt(2)
	ds_write_b128 v164, v[140:143] offset:55296
	s_waitcnt lgkmcnt(4)
	v_mfma_f32_32x32x16_bf16 v[112:127], v[168:171], v[144:147], v[112:127]
	s_waitcnt lgkmcnt(2)
	v_mfma_f32_32x32x16_bf16 v[96:111], v[182:185], v[144:147], v[96:111]
	v_mfma_f32_32x32x16_bf16 v[48:63], v[168:171], v[152:155], v[48:63]
	v_mfma_f32_32x32x16_bf16 v[32:47], v[182:185], v[152:155], v[32:47]
	v_mfma_f32_32x32x16_bf16 v[80:95], v[168:171], v[148:151], v[80:95]
	v_mfma_f32_32x32x16_bf16 v[64:79], v[182:185], v[148:151], v[64:79]
	v_mfma_f32_32x32x16_bf16 v[16:31], v[168:171], v[156:159], v[16:31]
	v_mfma_f32_32x32x16_bf16 v[0:15], v[182:185], v[156:159], v[0:15]
	ds_read_b128 v[136:139], v165 offset:96
	ds_read_b128 v[140:143], v165 offset:4704
	ds_read_b128 v[144:147], v165 offset:9312
	ds_read_b128 v[148:151], v165 offset:13920
	ds_read_b64_tr_b16 v[152:153], v172 offset:64512
	ds_read_b64_tr_b16 v[154:155], v217 offset:29952
	ds_read_b64_tr_b16 v[156:157], v172 offset:64576
	ds_read_b64_tr_b16 v[158:159], v217 offset:30016
	s_waitcnt vmcnt(1)
	ds_write_b128 v166, v[128:131] offset:27648
	s_waitcnt vmcnt(0)
	ds_write_b128 v164, v[132:135] offset:64512
	s_waitcnt lgkmcnt(0)
	s_barrier
	v_mfma_f32_32x32x16_bf16 v[112:127], v[152:155], v[136:139], v[112:127]
	v_mfma_f32_32x32x16_bf16 v[96:111], v[156:159], v[136:139], v[96:111]
	v_mfma_f32_32x32x16_bf16 v[48:63], v[152:155], v[144:147], v[48:63]
	v_mfma_f32_32x32x16_bf16 v[32:47], v[156:159], v[144:147], v[32:47]
	v_mfma_f32_32x32x16_bf16 v[80:95], v[152:155], v[140:143], v[80:95]
	v_mfma_f32_32x32x16_bf16 v[64:79], v[156:159], v[140:143], v[64:79]
	v_mfma_f32_32x32x16_bf16 v[16:31], v[152:155], v[148:151], v[16:31]
	v_mfma_f32_32x32x16_bf16 v[0:15], v[156:159], v[148:151], v[0:15]
	v_add3_u32 v156, s0, v167, v179
	v_add3_u32 v157, s0, v180, v181
	ds_read_b128 v[128:131], v156 offset:4608
	ds_read_b128 v[132:135], v156 offset:9216
	ds_read_b128 v[136:139], v156 offset:13824
	ds_read_b64_tr_b16 v[140:141], v157 offset:36864
	ds_read_b64_tr_b16 v[142:143], v157 offset:39168
	ds_read_b64_tr_b16 v[144:145], v157 offset:36928
	ds_read_b64_tr_b16 v[146:147], v157 offset:39232
	ds_read_b128 v[148:151], v156
	ds_read_b128 v[152:155], v156 offset:32
	v_add_u32_e32 v158, 0x9000, v157
	v_readlane_b32 s0, v253, 5
	v_readlane_b32 s1, v253, 6
	s_waitcnt lgkmcnt(1)
; template <int BM, class Epi>
; DI void gemm_tile(const bf16_t* __restrict__ A, int lda, const bf16_t* __restrict__ B, int ldb, int K, int row0, int col0, const Epi& epi, char* smem) {
;     ...
;     for (int kt = 0; kt < nk; ++kt) {
;         const char* cur = smem + (kt & 1) * GSTAGE;
;         char* nxt = smem + ((kt & 1) ^ 1) * GSTAGE;
;         const bool w1 = kt + 1 < nk, l2 = kt + 2 < nk;
;         const bf16_t* a2 = ag + (size_t)(kt + 2) * 64; const bf16_t* b2 = bg + (size_t)(kt + 2) * 64 * ldb;
; #pragma unroll
;         for (int s = 0; s < 4; ++s) {
;             bf16x8 xf[MI], wf[2];
; #pragma unroll
;             for (int mi = 0; mi < MI; ++mi) xf[mi] = *(const bf16x8*)(cur + xoff + mi * 32 * GA_S + s * 32);
; #pragma unroll
;             for (int ni = 0; ni < 2; ++ni) {
;                 const char* wp = cur + woff + s * 16 * GB_S + ni * 64;
;                 wf[ni] = cat8(tr_read(wp), tr_read(wp + 4 * GB_S));
;             }
; #pragma unroll
;             for (int mi = 0; mi < MI; ++mi)
; #pragma unroll
;                 for (int ni = 0; ni < 2; ++ni) acc[mi][ni] = mfma32(wf[ni], xf[mi], acc[mi][ni]);
;             if (w1) {
;                 if (s < NA_) *(u32x4*)(nxt + aw + 64 * s * GA_S) = ra[s];
;                 *(u32x4*)(nxt + bw + 16 * s * GB_S) = rb[s];
;             }
;             if (l2) {
;                 if (s < NA_) ra[s] = *(const u32x4*)(a2 + (size_t)(64 * s) * lda);
;                 rb[s] = *(const u32x4*)(b2 + (size_t)(16 * s) * ldb);
;             }
;         }
;         __syncthreads();
;     }
;     DI void operator()(const f32x16& a0, const f32x16& a1, int row, int cbase, int hh) const {
;         const int s = row < RL ? (row >> 13) : 4;
;         const float* gp = gate + s * 9216;
;         bf16_t* yp = Y + (size_t)row * 1024;
; #pragma unroll
;         for (int ni = 0; ni < 2; ++ni)
; #pragma unroll
;             for (int q4 = 0; q4 < 4; ++q4) {
;                 const int c = cbase + ni * 32 + 8 * q4 + 4 * hh;
;                 const f32x4 g = *(const f32x4*)(gp + c);
;                 const f32x16& v = ni ? a1 : a0;
;                 u32x2 w; w.x = pk2(coef * g[0] * v[4 * q4], coef * g[1] * v[4 * q4 + 1]); w.y = pk2(coef * g[2] * v[4 * q4 + 2], coef * g[3] * v[4 * q4 + 3]);
;                 *(u32x2*)(yp + c) = w;
;             }
	v_mfma_f32_32x32x16_bf16 v[112:127], v[140:143], v[148:151], v[112:127]
	v_mfma_f32_32x32x16_bf16 v[96:111], v[144:147], v[148:151], v[96:111]
	v_mfma_f32_32x32x16_bf16 v[48:63], v[140:143], v[132:135], v[48:63]
	v_mfma_f32_32x32x16_bf16 v[32:47], v[144:147], v[132:135], v[32:47]
	v_mfma_f32_32x32x16_bf16 v[80:95], v[140:143], v[128:131], v[80:95]
	v_mfma_f32_32x32x16_bf16 v[64:79], v[144:147], v[128:131], v[64:79]
	v_mfma_f32_32x32x16_bf16 v[16:31], v[140:143], v[136:139], v[16:31]
	v_mfma_f32_32x32x16_bf16 v[0:15], v[144:147], v[136:139], v[0:15]
	ds_read_b128 v[128:131], v156 offset:4640
	ds_read_b128 v[132:135], v156 offset:9248
	ds_read_b128 v[136:139], v156 offset:13856
	ds_read_b64_tr_b16 v[140:141], v157 offset:46080
	ds_read_b64_tr_b16 v[142:143], v157 offset:48384
	ds_read_b64_tr_b16 v[144:145], v157 offset:46144
	ds_read_b64_tr_b16 v[146:147], v157 offset:48448
	s_waitcnt lgkmcnt(2)
	v_mfma_f32_32x32x16_bf16 v[112:127], v[140:143], v[152:155], v[112:127]
	s_waitcnt lgkmcnt(0)
	v_mfma_f32_32x32x16_bf16 v[96:111], v[144:147], v[152:155], v[96:111]
	v_mfma_f32_32x32x16_bf16 v[48:63], v[140:143], v[132:135], v[48:63]
	v_mfma_f32_32x32x16_bf16 v[32:47], v[144:147], v[132:135], v[32:47]
	v_mfma_f32_32x32x16_bf16 v[80:95], v[140:143], v[128:131], v[80:95]
	v_mfma_f32_32x32x16_bf16 v[64:79], v[144:147], v[128:131], v[64:79]
	v_mfma_f32_32x32x16_bf16 v[16:31], v[140:143], v[136:139], v[16:31]
	v_mfma_f32_32x32x16_bf16 v[0:15], v[144:147], v[136:139], v[0:15]
	ds_read_b128 v[128:131], v156 offset:64
	ds_read_b128 v[132:135], v156 offset:4672
	ds_read_b128 v[136:139], v156 offset:9280
	ds_read_b128 v[140:143], v156 offset:13888
	ds_read_b64_tr_b16 v[144:145], v157 offset:55296
	ds_read_b64_tr_b16 v[146:147], v157 offset:57600
	ds_read_b64_tr_b16 v[148:149], v157 offset:55360
	ds_read_b64_tr_b16 v[150:151], v157 offset:57664
	s_waitcnt lgkmcnt(2)
	v_mfma_f32_32x32x16_bf16 v[112:127], v[144:147], v[128:131], v[112:127]
	s_waitcnt lgkmcnt(0)
	v_mfma_f32_32x32x16_bf16 v[96:111], v[148:151], v[128:131], v[96:111]
	v_mfma_f32_32x32x16_bf16 v[48:63], v[144:147], v[136:139], v[48:63]
	v_mfma_f32_32x32x16_bf16 v[32:47], v[148:151], v[136:139], v[32:47]
	v_mfma_f32_32x32x16_bf16 v[80:95], v[144:147], v[132:135], v[80:95]
	v_mfma_f32_32x32x16_bf16 v[64:79], v[148:151], v[132:135], v[64:79]
	v_mfma_f32_32x32x16_bf16 v[16:31], v[144:147], v[140:143], v[16:31]
	v_mfma_f32_32x32x16_bf16 v[0:15], v[148:151], v[140:143], v[0:15]
	ds_read_b128 v[128:131], v156 offset:96
	ds_read_b128 v[132:135], v156 offset:4704
	ds_read_b128 v[136:139], v156 offset:9312
	ds_read_b128 v[140:143], v156 offset:13920
	ds_read_b64_tr_b16 v[144:145], v157 offset:64512
	ds_read_b64_tr_b16 v[146:147], v158 offset:29952
	ds_read_b64_tr_b16 v[148:149], v157 offset:64576
	ds_read_b64_tr_b16 v[150:151], v158 offset:30016
	s_waitcnt lgkmcnt(0)
	s_barrier
	v_mfma_f32_32x32x16_bf16 v[112:127], v[144:147], v[128:131], v[112:127]
	v_mfma_f32_32x32x16_bf16 v[96:111], v[148:151], v[128:131], v[96:111]
	v_or_b32_e32 v128, s16, v176
	v_and_b32_e32 v129, 0xc0, v175
	v_add_u32_e32 v128, v128, v178
	v_lshlrev_b32_e32 v130, 2, v177
	v_mfma_f32_32x32x16_bf16 v[48:63], v[144:147], v[136:139], v[48:63]
	v_mfma_f32_32x32x16_bf16 v[32:47], v[148:151], v[136:139], v[32:47]
	v_or3_b32 v138, v130, v129, s10
	v_min_i32_e32 v129, 0x8000, v128
	v_ashrrev_i32_e32 v129, 13, v129
	v_mul_i32_i24_e32 v130, 0x2400, v129
	v_ashrrev_i32_e32 v131, 31, v130
	v_ashrrev_i32_e32 v129, 31, v128
	v_ashrrev_i32_e32 v139, 31, v138
	v_mfma_f32_32x32x16_bf16 v[80:95], v[144:147], v[132:135], v[80:95]
	v_mfma_f32_32x32x16_bf16 v[64:79], v[148:151], v[132:135], v[64:79]
	v_lshl_add_u64 v[132:133], v[130:131], 2, s[4:5]
	v_lshlrev_b64 v[130:131], 11, v[128:129]
	v_mfma_f32_32x32x16_bf16 v[16:31], v[144:147], v[140:143], v[16:31]
	v_mfma_f32_32x32x16_bf16 v[0:15], v[148:151], v[140:143], v[0:15]
	v_lshl_add_u64 v[140:141], s[0:1], 0, v[130:131]
	v_lshlrev_b64 v[130:131], 2, v[138:139]
	v_lshl_add_u64 v[132:133], v[132:133], 0, v[130:131]
	global_load_dwordx4 v[134:137], v[132:133], off
	s_waitcnt vmcnt(0)
	v_pk_mul_f32 v[134:135], v[134:135], 0.5 op_sel_hi:[1,0]
	s_nop 0
	v_pk_mul_f32 v[112:113], v[112:113], v[134:135]
	s_nop 0
	v_cvt_pk_bf16_f32 v134, v112, v113
	v_pk_mul_f32 v[112:113], v[136:137], 0.5 op_sel_hi:[1,0]
	s_nop 0
	v_pk_mul_f32 v[112:113], v[114:115], v[112:113]
	s_nop 0
	v_cvt_pk_bf16_f32 v135, v112, v113
	v_lshlrev_b64 v[112:113], 1, v[138:139]
	v_lshl_add_u64 v[138:139], v[140:141], 0, v[112:113]
	global_store_dwordx2 v[138:139], v[134:135], off
	global_load_dwordx4 v[134:137], v[132:133], off offset:32
	s_waitcnt vmcnt(0)
	v_pk_mul_f32 v[114:115], v[134:135], 0.5 op_sel_hi:[1,0]
	s_nop 0
	v_pk_mul_f32 v[114:115], v[116:117], v[114:115]
	v_pk_mul_f32 v[116:117], v[136:137], 0.5 op_sel_hi:[1,0]
	v_cvt_pk_bf16_f32 v114, v114, v115
	v_pk_mul_f32 v[116:117], v[118:119], v[116:117]
	s_nop 0
	v_cvt_pk_bf16_f32 v115, v116, v117
	global_store_dwordx2 v[138:139], v[114:115], off offset:16
	global_load_dwordx4 v[114:117], v[132:133], off offset:64
	s_waitcnt vmcnt(0)
	v_pk_mul_f32 v[114:115], v[114:115], 0.5 op_sel_hi:[1,0]
	v_pk_mul_f32 v[116:117], v[116:117], 0.5 op_sel_hi:[1,0]
	v_pk_mul_f32 v[114:115], v[120:121], v[114:115]
	v_pk_mul_f32 v[116:117], v[122:123], v[116:117]
	v_cvt_pk_bf16_f32 v114, v114, v115
	v_cvt_pk_bf16_f32 v115, v116, v117
	global_store_dwordx2 v[138:139], v[114:115], off offset:32
	global_load_dwordx4 v[114:117], v[132:133], off offset:96
	s_waitcnt vmcnt(0)
; DI unsigned pk2(float a, float b) { f32x2 v = {a, b}; bfx2 r = __builtin_convertvector(v, bfx2); return __builtin_bit_cast(unsigned, r); }
;     DI void operator()(const f32x16& a0, const f32x16& a1, int row, int cbase, int hh) const {
;         const int s = row < RL ? (row >> 13) : 4;
;         const float* gp = gate + s * 9216;
;         bf16_t* yp = Y + (size_t)row * 1024;
; #pragma unroll
;         for (int ni = 0; ni < 2; ++ni)
; #pragma unroll
;             for (int q4 = 0; q4 < 4; ++q4) {
;                 const int c = cbase + ni * 32 + 8 * q4 + 4 * hh;
;                 const f32x4 g = *(const f32x4*)(gp + c);
;                 const f32x16& v = ni ? a1 : a0;
;                 u32x2 w; w.x = pk2(coef * g[0] * v[4 * q4], coef * g[1] * v[4 * q4 + 1]); w.y = pk2(coef * g[2] * v[4 * q4 + 2], coef * g[3] * v[4 * q4 + 3]);
;                 *(u32x2*)(yp + c) = w;
;             }
	v_pk_mul_f32 v[114:115], v[114:115], 0.5 op_sel_hi:[1,0]
	v_pk_mul_f32 v[116:117], v[116:117], 0.5 op_sel_hi:[1,0]
	v_pk_mul_f32 v[114:115], v[124:125], v[114:115]
	v_pk_mul_f32 v[116:117], v[126:127], v[116:117]
	v_cvt_pk_bf16_f32 v114, v114, v115
	v_cvt_pk_bf16_f32 v115, v116, v117
	global_store_dwordx2 v[138:139], v[114:115], off offset:48
	global_load_dwordx4 v[114:117], v[132:133], off offset:128
	s_waitcnt vmcnt(0)
	v_pk_mul_f32 v[114:115], v[114:115], 0.5 op_sel_hi:[1,0]
	s_nop 0
	v_pk_mul_f32 v[96:97], v[96:97], v[114:115]
	v_pk_mul_f32 v[114:115], v[116:117], 0.5 op_sel_hi:[1,0]
	v_cvt_pk_bf16_f32 v96, v96, v97
	v_pk_mul_f32 v[98:99], v[98:99], v[114:115]
	s_nop 0
	v_cvt_pk_bf16_f32 v97, v98, v99
	global_store_dwordx2 v[138:139], v[96:97], off offset:64
	global_load_dwordx4 v[96:99], v[132:133], off offset:160
	s_waitcnt vmcnt(0)
	v_pk_mul_f32 v[96:97], v[96:97], 0.5 op_sel_hi:[1,0]
	v_pk_mul_f32 v[98:99], v[98:99], 0.5 op_sel_hi:[1,0]
	v_pk_mul_f32 v[96:97], v[100:101], v[96:97]
	v_pk_mul_f32 v[98:99], v[102:103], v[98:99]
	v_cvt_pk_bf16_f32 v96, v96, v97
	v_cvt_pk_bf16_f32 v97, v98, v99
	global_store_dwordx2 v[138:139], v[96:97], off offset:80
	global_load_dwordx4 v[96:99], v[132:133], off offset:192
	s_waitcnt vmcnt(0)
	v_pk_mul_f32 v[96:97], v[96:97], 0.5 op_sel_hi:[1,0]
	v_pk_mul_f32 v[98:99], v[98:99], 0.5 op_sel_hi:[1,0]
	v_pk_mul_f32 v[96:97], v[104:105], v[96:97]
	v_pk_mul_f32 v[98:99], v[106:107], v[98:99]
	v_cvt_pk_bf16_f32 v96, v96, v97
	v_cvt_pk_bf16_f32 v97, v98, v99
	global_store_dwordx2 v[138:139], v[96:97], off offset:96
	global_load_dwordx4 v[96:99], v[132:133], off offset:224
	s_waitcnt vmcnt(0)
	v_pk_mul_f32 v[96:97], v[96:97], 0.5 op_sel_hi:[1,0]
	v_pk_mul_f32 v[98:99], v[98:99], 0.5 op_sel_hi:[1,0]
	v_pk_mul_f32 v[96:97], v[108:109], v[96:97]
	v_pk_mul_f32 v[98:99], v[110:111], v[98:99]
	v_cvt_pk_bf16_f32 v96, v96, v97
	v_cvt_pk_bf16_f32 v97, v98, v99
	global_store_dwordx2 v[138:139], v[96:97], off offset:112
	v_or_b32_e32 v96, 32, v128
	v_min_i32_e32 v97, 0x8000, v96
	v_ashrrev_i32_e32 v97, 13, v97
	v_mul_i32_i24_e32 v98, 0x2400, v97
	v_ashrrev_i32_e32 v99, 31, v98
	v_ashrrev_i32_e32 v97, 31, v96
	v_lshl_add_u64 v[98:99], v[98:99], 2, s[4:5]
	v_lshlrev_b64 v[96:97], 11, v[96:97]
	v_lshl_add_u64 v[102:103], s[0:1], 0, v[96:97]
	v_lshl_add_u64 v[96:97], v[98:99], 0, v[130:131]
	global_load_dwordx4 v[98:101], v[96:97], off
	s_waitcnt vmcnt(0)
	v_pk_mul_f32 v[98:99], v[98:99], 0.5 op_sel_hi:[1,0]
	s_nop 0
	v_pk_mul_f32 v[80:81], v[80:81], v[98:99]
	v_pk_mul_f32 v[98:99], v[100:101], 0.5 op_sel_hi:[1,0]
	v_cvt_pk_bf16_f32 v80, v80, v81
	v_pk_mul_f32 v[82:83], v[82:83], v[98:99]
	v_lshl_add_u64 v[98:99], v[102:103], 0, v[112:113]
	v_cvt_pk_bf16_f32 v81, v82, v83
	global_store_dwordx2 v[98:99], v[80:81], off
	global_load_dwordx4 v[80:83], v[96:97], off offset:32
	s_waitcnt vmcnt(0)
	v_pk_mul_f32 v[80:81], v[80:81], 0.5 op_sel_hi:[1,0]
	v_pk_mul_f32 v[82:83], v[82:83], 0.5 op_sel_hi:[1,0]
	v_pk_mul_f32 v[80:81], v[84:85], v[80:81]
	v_pk_mul_f32 v[82:83], v[86:87], v[82:83]
	v_cvt_pk_bf16_f32 v80, v80, v81
	v_cvt_pk_bf16_f32 v81, v82, v83
	global_store_dwordx2 v[98:99], v[80:81], off offset:16
	global_load_dwordx4 v[80:83], v[96:97], off offset:64
	s_waitcnt vmcnt(0)
	v_pk_mul_f32 v[80:81], v[80:81], 0.5 op_sel_hi:[1,0]
	v_pk_mul_f32 v[82:83], v[82:83], 0.5 op_sel_hi:[1,0]
	v_pk_mul_f32 v[80:81], v[88:89], v[80:81]
	v_pk_mul_f32 v[82:83], v[90:91], v[82:83]
	v_cvt_pk_bf16_f32 v80, v80, v81
	v_cvt_pk_bf16_f32 v81, v82, v83
	global_store_dwordx2 v[98:99], v[80:81], off offset:32
	global_load_dwordx4 v[80:83], v[96:97], off offset:96
	s_waitcnt vmcnt(0)
	v_pk_mul_f32 v[80:81], v[80:81], 0.5 op_sel_hi:[1,0]
	v_pk_mul_f32 v[82:83], v[82:83], 0.5 op_sel_hi:[1,0]
	v_pk_mul_f32 v[80:81], v[92:93], v[80:81]
	v_pk_mul_f32 v[82:83], v[94:95], v[82:83]
	v_cvt_pk_bf16_f32 v80, v80, v81
	v_cvt_pk_bf16_f32 v81, v82, v83
	global_store_dwordx2 v[98:99], v[80:81], off offset:48
	global_load_dwordx4 v[80:83], v[96:97], off offset:128
	s_waitcnt vmcnt(0)
	v_pk_mul_f32 v[80:81], v[80:81], 0.5 op_sel_hi:[1,0]
	s_nop 0
	v_pk_mul_f32 v[64:65], v[64:65], v[80:81]
	v_pk_mul_f32 v[80:81], v[82:83], 0.5 op_sel_hi:[1,0]
	v_cvt_pk_bf16_f32 v64, v64, v65
	v_pk_mul_f32 v[66:67], v[66:67], v[80:81]
	s_nop 0
	v_cvt_pk_bf16_f32 v65, v66, v67
	global_store_dwordx2 v[98:99], v[64:65], off offset:64
	global_load_dwordx4 v[64:67], v[96:97], off offset:160
	s_waitcnt vmcnt(0)
	v_pk_mul_f32 v[64:65], v[64:65], 0.5 op_sel_hi:[1,0]
	v_pk_mul_f32 v[66:67], v[66:67], 0.5 op_sel_hi:[1,0]
	v_pk_mul_f32 v[64:65], v[68:69], v[64:65]
	v_pk_mul_f32 v[66:67], v[70:71], v[66:67]
	v_cvt_pk_bf16_f32 v64, v64, v65
	v_cvt_pk_bf16_f32 v65, v66, v67
	global_store_dwordx2 v[98:99], v[64:65], off offset:80
	global_load_dwordx4 v[64:67], v[96:97], off offset:192
	s_waitcnt vmcnt(0)
	v_pk_mul_f32 v[64:65], v[64:65], 0.5 op_sel_hi:[1,0]
	v_pk_mul_f32 v[66:67], v[66:67], 0.5 op_sel_hi:[1,0]
	v_pk_mul_f32 v[64:65], v[72:73], v[64:65]
	v_pk_mul_f32 v[66:67], v[74:75], v[66:67]
	v_cvt_pk_bf16_f32 v64, v64, v65
	v_cvt_pk_bf16_f32 v65, v66, v67
	global_store_dwordx2 v[98:99], v[64:65], off offset:96
	global_load_dwordx4 v[64:67], v[96:97], off offset:224
	s_waitcnt vmcnt(0)
	v_pk_mul_f32 v[64:65], v[64:65], 0.5 op_sel_hi:[1,0]
	v_pk_mul_f32 v[66:67], v[66:67], 0.5 op_sel_hi:[1,0]
	v_pk_mul_f32 v[64:65], v[76:77], v[64:65]
	v_pk_mul_f32 v[66:67], v[78:79], v[66:67]
	v_cvt_pk_bf16_f32 v64, v64, v65
	v_cvt_pk_bf16_f32 v65, v66, v67
	global_store_dwordx2 v[98:99], v[64:65], off offset:112
	v_or_b32_e32 v64, 64, v128
	v_min_i32_e32 v65, 0x8000, v64
	v_ashrrev_i32_e32 v65, 13, v65
	v_mul_i32_i24_e32 v66, 0x2400, v65
	v_ashrrev_i32_e32 v67, 31, v66
	v_ashrrev_i32_e32 v65, 31, v64
	v_lshl_add_u64 v[66:67], v[66:67], 2, s[4:5]
	v_lshlrev_b64 v[64:65], 11, v[64:65]
	v_lshl_add_u64 v[70:71], s[0:1], 0, v[64:65]
	v_lshl_add_u64 v[64:65], v[66:67], 0, v[130:131]
	global_load_dwordx4 v[66:69], v[64:65], off
	s_waitcnt vmcnt(0)
; DI unsigned pk2(float a, float b) { f32x2 v = {a, b}; bfx2 r = __builtin_convertvector(v, bfx2); return __builtin_bit_cast(unsigned, r); }
;     DI void operator()(const f32x16& a0, const f32x16& a1, int row, int cbase, int hh) const {
;         const int s = row < RL ? (row >> 13) : 4;
;         const float* gp = gate + s * 9216;
;         bf16_t* yp = Y + (size_t)row * 1024;
; #pragma unroll
;         for (int ni = 0; ni < 2; ++ni)
; #pragma unroll
;             for (int q4 = 0; q4 < 4; ++q4) {
;                 const int c = cbase + ni * 32 + 8 * q4 + 4 * hh;
;                 const f32x4 g = *(const f32x4*)(gp + c);
;                 const f32x16& v = ni ? a1 : a0;
;                 u32x2 w; w.x = pk2(coef * g[0] * v[4 * q4], coef * g[1] * v[4 * q4 + 1]); w.y = pk2(coef * g[2] * v[4 * q4 + 2], coef * g[3] * v[4 * q4 + 3]);
;                 *(u32x2*)(yp + c) = w;
;             }
	v_pk_mul_f32 v[66:67], v[66:67], 0.5 op_sel_hi:[1,0]
	s_nop 0
	v_pk_mul_f32 v[48:49], v[48:49], v[66:67]
	v_pk_mul_f32 v[66:67], v[68:69], 0.5 op_sel_hi:[1,0]
	v_cvt_pk_bf16_f32 v48, v48, v49
	v_pk_mul_f32 v[50:51], v[50:51], v[66:67]
	v_lshl_add_u64 v[66:67], v[70:71], 0, v[112:113]
	v_cvt_pk_bf16_f32 v49, v50, v51
	global_store_dwordx2 v[66:67], v[48:49], off
	global_load_dwordx4 v[48:51], v[64:65], off offset:32
	s_waitcnt vmcnt(0)
	v_pk_mul_f32 v[48:49], v[48:49], 0.5 op_sel_hi:[1,0]
	v_pk_mul_f32 v[50:51], v[50:51], 0.5 op_sel_hi:[1,0]
	v_pk_mul_f32 v[48:49], v[52:53], v[48:49]
	v_pk_mul_f32 v[50:51], v[54:55], v[50:51]
	v_cvt_pk_bf16_f32 v48, v48, v49
	v_cvt_pk_bf16_f32 v49, v50, v51
	global_store_dwordx2 v[66:67], v[48:49], off offset:16
	global_load_dwordx4 v[48:51], v[64:65], off offset:64
	s_waitcnt vmcnt(0)
	v_pk_mul_f32 v[48:49], v[48:49], 0.5 op_sel_hi:[1,0]
	v_pk_mul_f32 v[50:51], v[50:51], 0.5 op_sel_hi:[1,0]
	v_pk_mul_f32 v[48:49], v[56:57], v[48:49]
	v_pk_mul_f32 v[50:51], v[58:59], v[50:51]
	v_cvt_pk_bf16_f32 v48, v48, v49
	v_cvt_pk_bf16_f32 v49, v50, v51
	global_store_dwordx2 v[66:67], v[48:49], off offset:32
	global_load_dwordx4 v[48:51], v[64:65], off offset:96
	s_waitcnt vmcnt(0)
	v_pk_mul_f32 v[48:49], v[48:49], 0.5 op_sel_hi:[1,0]
	v_pk_mul_f32 v[50:51], v[50:51], 0.5 op_sel_hi:[1,0]
	v_pk_mul_f32 v[48:49], v[60:61], v[48:49]
	v_pk_mul_f32 v[50:51], v[62:63], v[50:51]
	v_cvt_pk_bf16_f32 v48, v48, v49
	v_cvt_pk_bf16_f32 v49, v50, v51
	global_store_dwordx2 v[66:67], v[48:49], off offset:48
	global_load_dwordx4 v[48:51], v[64:65], off offset:128
	s_waitcnt vmcnt(0)
	v_pk_mul_f32 v[48:49], v[48:49], 0.5 op_sel_hi:[1,0]
	s_nop 0
	v_pk_mul_f32 v[32:33], v[32:33], v[48:49]
	v_pk_mul_f32 v[48:49], v[50:51], 0.5 op_sel_hi:[1,0]
	v_cvt_pk_bf16_f32 v32, v32, v33
	v_pk_mul_f32 v[34:35], v[34:35], v[48:49]
	s_nop 0
	v_cvt_pk_bf16_f32 v33, v34, v35
	global_store_dwordx2 v[66:67], v[32:33], off offset:64
	global_load_dwordx4 v[32:35], v[64:65], off offset:160
	s_waitcnt vmcnt(0)
	v_pk_mul_f32 v[32:33], v[32:33], 0.5 op_sel_hi:[1,0]
	v_pk_mul_f32 v[34:35], v[34:35], 0.5 op_sel_hi:[1,0]
	v_pk_mul_f32 v[32:33], v[36:37], v[32:33]
	v_pk_mul_f32 v[34:35], v[38:39], v[34:35]
	v_cvt_pk_bf16_f32 v32, v32, v33
	v_cvt_pk_bf16_f32 v33, v34, v35
	global_store_dwordx2 v[66:67], v[32:33], off offset:80
	global_load_dwordx4 v[32:35], v[64:65], off offset:192
	s_waitcnt vmcnt(0)
	v_pk_mul_f32 v[32:33], v[32:33], 0.5 op_sel_hi:[1,0]
	v_pk_mul_f32 v[34:35], v[34:35], 0.5 op_sel_hi:[1,0]
	v_pk_mul_f32 v[32:33], v[40:41], v[32:33]
	v_pk_mul_f32 v[34:35], v[42:43], v[34:35]
	v_cvt_pk_bf16_f32 v32, v32, v33
	v_cvt_pk_bf16_f32 v33, v34, v35
	global_store_dwordx2 v[66:67], v[32:33], off offset:96
	global_load_dwordx4 v[32:35], v[64:65], off offset:224
	s_waitcnt vmcnt(0)
	v_pk_mul_f32 v[32:33], v[32:33], 0.5 op_sel_hi:[1,0]
	v_pk_mul_f32 v[34:35], v[34:35], 0.5 op_sel_hi:[1,0]
	v_pk_mul_f32 v[32:33], v[44:45], v[32:33]
	v_pk_mul_f32 v[34:35], v[46:47], v[34:35]
	v_cvt_pk_bf16_f32 v32, v32, v33
	v_cvt_pk_bf16_f32 v33, v34, v35
	global_store_dwordx2 v[66:67], v[32:33], off offset:112
	v_or_b32_e32 v32, 0x60, v128
	v_min_i32_e32 v33, 0x8000, v32
	v_ashrrev_i32_e32 v33, 13, v33
	v_mul_i32_i24_e32 v34, 0x2400, v33
	v_ashrrev_i32_e32 v35, 31, v34
	v_ashrrev_i32_e32 v33, 31, v32
	v_lshl_add_u64 v[34:35], v[34:35], 2, s[4:5]
	v_lshlrev_b64 v[32:33], 11, v[32:33]
	v_lshl_add_u64 v[38:39], s[0:1], 0, v[32:33]
	v_lshl_add_u64 v[32:33], v[34:35], 0, v[130:131]
	global_load_dwordx4 v[34:37], v[32:33], off
	s_waitcnt vmcnt(0)
	v_pk_mul_f32 v[34:35], v[34:35], 0.5 op_sel_hi:[1,0]
	s_nop 0
	v_pk_mul_f32 v[16:17], v[16:17], v[34:35]
	v_pk_mul_f32 v[34:35], v[36:37], 0.5 op_sel_hi:[1,0]
	v_cvt_pk_bf16_f32 v16, v16, v17
	v_pk_mul_f32 v[18:19], v[18:19], v[34:35]
	v_lshl_add_u64 v[34:35], v[38:39], 0, v[112:113]
	v_cvt_pk_bf16_f32 v17, v18, v19
	global_store_dwordx2 v[34:35], v[16:17], off
	global_load_dwordx4 v[16:19], v[32:33], off offset:32
	s_waitcnt vmcnt(0)
	v_pk_mul_f32 v[16:17], v[16:17], 0.5 op_sel_hi:[1,0]
	v_pk_mul_f32 v[18:19], v[18:19], 0.5 op_sel_hi:[1,0]
	v_pk_mul_f32 v[16:17], v[20:21], v[16:17]
	v_pk_mul_f32 v[18:19], v[22:23], v[18:19]
	v_cvt_pk_bf16_f32 v16, v16, v17
	v_cvt_pk_bf16_f32 v17, v18, v19
	global_store_dwordx2 v[34:35], v[16:17], off offset:16
	global_load_dwordx4 v[16:19], v[32:33], off offset:64
	s_waitcnt vmcnt(0)
	v_pk_mul_f32 v[16:17], v[16:17], 0.5 op_sel_hi:[1,0]
	v_pk_mul_f32 v[18:19], v[18:19], 0.5 op_sel_hi:[1,0]
	v_pk_mul_f32 v[16:17], v[24:25], v[16:17]
	v_pk_mul_f32 v[18:19], v[26:27], v[18:19]
	v_cvt_pk_bf16_f32 v16, v16, v17
	v_cvt_pk_bf16_f32 v17, v18, v19
	global_store_dwordx2 v[34:35], v[16:17], off offset:32
	global_load_dwordx4 v[16:19], v[32:33], off offset:96
	s_waitcnt vmcnt(0)
	v_pk_mul_f32 v[16:17], v[16:17], 0.5 op_sel_hi:[1,0]
	v_pk_mul_f32 v[18:19], v[18:19], 0.5 op_sel_hi:[1,0]
	v_pk_mul_f32 v[16:17], v[28:29], v[16:17]
	v_pk_mul_f32 v[18:19], v[30:31], v[18:19]
	v_cvt_pk_bf16_f32 v16, v16, v17
	v_cvt_pk_bf16_f32 v17, v18, v19
	global_store_dwordx2 v[34:35], v[16:17], off offset:48
	global_load_dwordx4 v[16:19], v[32:33], off offset:128
	s_waitcnt vmcnt(0)
	v_pk_mul_f32 v[16:17], v[16:17], 0.5 op_sel_hi:[1,0]
	s_nop 0
	v_pk_mul_f32 v[0:1], v[0:1], v[16:17]
	v_pk_mul_f32 v[16:17], v[18:19], 0.5 op_sel_hi:[1,0]
	v_cvt_pk_bf16_f32 v0, v0, v1
	v_pk_mul_f32 v[2:3], v[2:3], v[16:17]
	s_nop 0
	v_cvt_pk_bf16_f32 v1, v2, v3
	global_store_dwordx2 v[34:35], v[0:1], off offset:64
	global_load_dwordx4 v[0:3], v[32:33], off offset:160
	s_waitcnt vmcnt(0)
	v_pk_mul_f32 v[0:1], v[0:1], 0.5 op_sel_hi:[1,0]
	v_pk_mul_f32 v[2:3], v[2:3], 0.5 op_sel_hi:[1,0]
	v_pk_mul_f32 v[0:1], v[4:5], v[0:1]
	v_pk_mul_f32 v[2:3], v[6:7], v[2:3]
	v_cvt_pk_bf16_f32 v0, v0, v1
	v_cvt_pk_bf16_f32 v1, v2, v3
	global_store_dwordx2 v[34:35], v[0:1], off offset:80
	global_load_dwordx4 v[0:3], v[32:33], off offset:192
	s_waitcnt vmcnt(0)
	v_pk_mul_f32 v[0:1], v[0:1], 0.5 op_sel_hi:[1,0]
	v_pk_mul_f32 v[2:3], v[2:3], 0.5 op_sel_hi:[1,0]
	v_pk_mul_f32 v[0:1], v[8:9], v[0:1]
	v_pk_mul_f32 v[2:3], v[10:11], v[2:3]
	v_cvt_pk_bf16_f32 v0, v0, v1
	v_cvt_pk_bf16_f32 v1, v2, v3
	global_store_dwordx2 v[34:35], v[0:1], off offset:96
	global_load_dwordx4 v[0:3], v[32:33], off offset:224
	s_waitcnt vmcnt(0)
	v_pk_mul_f32 v[0:1], v[0:1], 0.5 op_sel_hi:[1,0]
	v_pk_mul_f32 v[2:3], v[2:3], 0.5 op_sel_hi:[1,0]
	v_pk_mul_f32 v[0:1], v[12:13], v[0:1]
	v_pk_mul_f32 v[2:3], v[14:15], v[2:3]
	v_cvt_pk_bf16_f32 v0, v0, v1
	v_cvt_pk_bf16_f32 v1, v2, v3
	global_store_dwordx2 v[34:35], v[0:1], off offset:112
	s_cbranch_scc0 .LBB0_1482
